# P7: pairs of K=16 bf16 MFMAs fused into K=32 16x16x32 bf16 (U pairs v108:111/v112:115, B quads permuted once in prologue)
# speedup vs baseline: 1.0250x; 1.0250x over previous
; template <int DIR>
; __device__ __forceinline__ void s5_local_dir(const bf16_t* UZ, unsigned char* ws, int gw, int NGW, int lane) {
;     ...
;     const int pair = gw & 127, g = pair & 63, fr = lane & 15, fq = lane >> 4;
;     const bf16_t* Bb = (const bf16_t*)(ws + WS_BB) + (size_t)pair * 128 * 16;
;     bf16x4 Bre[4][4], Bim[4][4]; float a1r[4], a1i[4], a64r[4], a64i[4], wr_[4], wi_[4];
; #pragma unroll
;     for (int t = 0; t < 4; ++t) {
;         const int p = 16 * t + fr;
;         const bf16x4 b_re = *(const bf16x4*)(Bb + (2 * p) * 16 + 4 * fq), b_im = *(const bf16x4*)(Bb + (2 * p + 1) * 16 + 4 * fq);
;         const f32x4 ap = ((const f32x4*)(ws + WS_APOW))[pair * 64 + p];
;         const float ar = ap.x, ai = ap.y;
;         float r2 = ar, i2 = ai; cmul(r2, i2, ar, ai);
;         float r4 = r2, i4 = i2; cmul(r4, i4, r2, i2);
;         float r8 = r4, i8 = i4; cmul(r8, i8, r4, i4);
;         float r12 = r8, i12 = i8; cmul(r12, i12, r4, i4);
;         float r16 = r8, i16 = i8; cmul(r16, i16, r8, i8);
;         float r32 = r16, i32 = i16; cmul(r32, i32, r16, i16);
;         float r48 = r32, i48 = i32; cmul(r48, i48, r16, i16);
;         a1r[t] = ar; a1i[t] = ai; a64r[t] = ap.z; a64i[t] = ap.w;
;         const int e = DIR ? fq : 3 - fq;
;         wr_[t] = e == 0 ? 1.f : e == 1 ? r4 : e == 2 ? r8 : r12; wi_[t] = e == 0 ? 0.f : e == 1 ? i4 : e == 2 ? i8 : i12;
; #pragma unroll
;         for (int m = 0; m < 4; ++m) {
;             const int em = DIR ? m : 3 - m;
;             const float pr = em == 0 ? 1.f : em == 1 ? r16 : em == 2 ? r32 : r48, pi = em == 0 ? 0.f : em == 1 ? i16 : em == 2 ? i32 : i48;
;             Bre[m][t] = cscale_bf(b_re, b_im, pr, pi, false); Bim[m][t] = cscale_bf(b_re, b_im, pr, pi, true);
;         }
;     }
;     const int qd = gw >> 7, b = qd >> 2, q = qd & 3;
;     if (qd >= 16) return;
;     const int c0 = 17 * q, c1 = q < 3 ? c0 + 17 : 67;
;     float Rr[4] = {0.f, 0.f, 0.f, 0.f}, Ri[4] = {0.f, 0.f, 0.f, 0.f};
;     float* ebase = E + ((size_t)((b * 2 + DIR) * 64 + g) * NCHUNK) * 128;
;     bf16x4 Un[4];
;     load_uf(Un, UZ, chunk_rowbase(b, DIR, c0), g, lane);
.LBB0_644:
	s_cmp_lt_i32 s68, 8
	s_cselect_b64 s[0:1], -1, 0
	s_and_b64 s[0:1], s[0:1], s[2:3]
	s_andn2_b64 vcc, exec, s[0:1]
	s_cbranch_vccnz .LBB0_690
	v_readfirstlane_b32 s2, v192
	s_lshr_b32 s40, s2, 6
	s_lshl_b32 s2, s12, 3
	s_add_i32 s40, s40, s2
	s_and_b32 s2, s40, 64
	s_add_u32 s41, s30, 0x100000
	s_addc_u32 s42, s31, 0
	s_add_u32 s4, s30, 0x80000
	s_addc_u32 s5, s31, 0
	v_and_b32_e32 v127, 15, v192
	v_bfe_u32 v128, v192, 4, 2
	v_and_b32_e32 v126, 63, v192
	s_cmp_eq_u32 s2, 0
	v_lshlrev_b32_e32 v129, 2, v128
	v_lshlrev_b32_e32 v130, 5, v127
	s_cbranch_scc1 .LBB0_662
	s_ashr_i32 s2, s40, 7
	s_cmp_lt_i32 s2, 16
	s_mov_b64 s[22:23], 0
	s_cbranch_scc0 .LBB0_663
	s_and_b32 s43, s2, 3
	s_mul_i32 s38, s43, 17
	s_ashr_i32 s36, s40, 9
	s_and_b32 s44, s40, 63
	s_add_i32 s37, s38, 17
	s_cmp_lg_u32 s43, 3
	s_cselect_b64 s[24:25], -1, 0
	s_and_b64 s[2:3], s[24:25], exec
	s_cselect_b32 s46, s37, 0x43
	s_lshl_b32 s45, s36, 7
	v_cmp_gt_u32_e64 s[8:9], 16, v126
	v_mov_b32_e32 v115, 0
	v_mov_b32_e32 v240, 0
	v_mov_b32_e32 v241, 0
	s_cmp_ge_u32 s38, s46
	v_mov_b32_e32 v114, 0
	v_mov_b32_e32 v112, 0
	v_mov_b32_e32 v110, 0
	v_mov_b32_e32 v113, 0
	v_mov_b32_e32 v111, 0
	v_mov_b32_e32 v109, 0
	v_mov_b32_e32 v108, 0
	s_cbranch_scc1 .LBB0_684
	s_and_b32 s37, s40, 0x7f
	s_lshl_b32 s2, s37, 12
	s_add_u32 s2, s41, s2
	s_addc_u32 s3, s42, 0
	s_lshl_b32 s37, s37, 6
	s_waitcnt vmcnt(0)
	v_or_b32_e32 v0, s37, v127
	v_lshlrev_b32_e32 v0, 4, v0
	global_load_dwordx4 v[0:3], v0, s[4:5]
	v_lshlrev_b32_e32 v16, 1, v130
	v_mov_b32_e32 v17, 0
	v_lshl_add_u64 v[4:5], s[2:3], 0, v[16:17]
	v_lshlrev_b32_e32 v16, 1, v129
	v_lshl_add_u64 v[4:5], v[4:5], 0, v[16:17]
	global_load_dwordx2 v[22:23], v[4:5], off
	global_load_dwordx2 v[26:27], v[4:5], off offset:32
	v_or_b32_e32 v10, 16, v127
	v_or_b32_e32 v11, 32, v127
	v_or_b32_e32 v12, 48, v126
	v_lshlrev_b32_e32 v4, 6, v10
	v_mov_b32_e32 v5, v17
	v_lshlrev_b32_e32 v6, 6, v11
	v_mov_b32_e32 v7, v17
	v_lshlrev_b32_e32 v8, 6, v12
	v_mov_b32_e32 v9, v17
	v_lshl_add_u64 v[4:5], s[2:3], 0, v[4:5]
	v_lshrrev_b32_e32 v13, 1, v192
	v_or_b32_e32 v10, s37, v10
	v_lshl_add_u64 v[6:7], s[2:3], 0, v[6:7]
	v_or_b32_e32 v11, s37, v11
	v_lshl_add_u64 v[8:9], s[2:3], 0, v[8:9]
	v_or_b32_e32 v12, s37, v12
	v_lshl_add_u64 v[18:19], v[4:5], 0, v[16:17]
	v_lshlrev_b32_e32 v28, 4, v10
	v_lshl_add_u64 v[20:21], v[6:7], 0, v[16:17]
	v_lshlrev_b32_e32 v29, 4, v11
	v_lshl_add_u64 v[24:25], v[8:9], 0, v[16:17]
	v_lshlrev_b32_e32 v30, 4, v12
	v_and_b32_e32 v16, 24, v13
	global_load_dwordx2 v[50:51], v[18:19], off
	global_load_dwordx2 v[48:49], v[18:19], off offset:32
	global_load_dwordx4 v[4:7], v28, s[4:5]
	global_load_dwordx2 v[72:73], v[20:21], off
	global_load_dwordx2 v[70:71], v[20:21], off offset:32
	global_load_dwordx4 v[8:11], v29, s[4:5]
	global_load_dwordx2 v[94:95], v[24:25], off
	global_load_dwordx2 v[92:93], v[24:25], off offset:32
	global_load_dwordx4 v[12:15], v30, s[4:5]
	s_lshl_b32 s98, s36, 8
	s_addk_i32 s98, 0x40c0
	s_lshl_b32 s99, s36, 12
	s_addk_i32 s99, 0x10c0
	s_cmp_eq_u32 s43, 0
	s_cselect_b32 s98, s98, s99
	s_mul_i32 s99, s43, 0xfffffbc0
	s_lshl_b32 s100, s44, 5
	s_add_u32 s100, s18, s100
	s_addc_u32 s101, s19, 0
	v_or_b32_e32 v160, s99, v127
	v_add_u32_e32 v160, s98, v160
	v_ashrrev_i32_e32 v161, 31, v160
	v_lshlrev_b64 v[162:163], 12, v[160:161]
	v_lshrrev_b32_e32 v164, 1, v192
	v_and_b32_e32 v164, 24, v164
	v_mov_b32_e32 v165, 0
	v_lshl_add_u64 v[162:163], s[100:101], 0, v[162:163]
	v_lshl_add_u64 v[162:163], v[162:163], 0, v[164:165]
	s_mov_b32 s98, 0x10000
	s_mov_b32 s99, 0
	v_lshl_add_u64 v[164:165], v[162:163], 0, s[98:99]
	v_lshl_add_u64 v[166:167], v[164:165], 0, s[98:99]
	v_lshl_add_u64 v[168:169], v[166:167], 0, s[98:99]
	global_load_dwordx2 v[152:153], v[162:163], off
	global_load_dwordx2 v[154:155], v[164:165], off
	global_load_dwordx2 v[156:157], v[166:167], off
	global_load_dwordx2 v[158:159], v[168:169], off
	s_lshl_b32 s39, s44, 5
	s_add_u32 s2, s18, s39
	s_addc_u32 s3, s19, 0
	v_cmp_eq_u32_e32 vcc, 2, v128
	v_lshl_add_u64 v[18:19], s[2:3], 0, v[16:17]
	v_cmp_eq_u32_e64 s[2:3], 1, v128
	s_mov_b32 s37, 0x5040100
	s_lshl_b32 s47, s36, 8
	s_lshl_b32 s48, s36, 12
	s_addk_i32 s47, 0x40c0
	s_addk_i32 s48, 0x10c0
	s_cmp_eq_u32 s43, 0
	s_waitcnt vmcnt(15)
	v_pk_mul_f32 v[24:25], v[0:1], v[0:1] op_sel:[1,1] op_sel_hi:[1,0]
	s_nop 0
	v_pk_fma_f32 v[28:29], v[0:1], v[0:1], v[24:25] op_sel_hi:[1,0,1] neg_lo:[0,0,1] neg_hi:[0,0,1]
	v_pk_fma_f32 v[24:25], v[0:1], v[0:1], v[24:25] op_sel_hi:[1,0,1]
	v_mov_b32_e32 v30, v28
	v_pk_mov_b32 v[32:33], v[24:25], v[28:29] op_sel:[1,0]
	v_mov_b32_e32 v31, v25
	v_pk_mul_f32 v[24:25], v[24:25], v[32:33] op_sel:[1,0]
	v_mov_b32_e32 v20, v0
	v_pk_fma_f32 v[32:33], v[28:29], v[30:31], v[24:25] op_sel_hi:[0,1,1] neg_lo:[0,0,1] neg_hi:[0,0,1]
	v_pk_fma_f32 v[24:25], v[28:29], v[30:31], v[24:25] op_sel_hi:[0,1,1]
	v_pk_mov_b32 v[30:31], v[24:25], v[32:33] op_sel:[1,0]
	v_mov_b32_e32 v28, v32
	v_mov_b32_e32 v29, v25
	v_pk_mul_f32 v[30:31], v[24:25], v[30:31] op_sel:[1,0]
	v_mov_b32_e32 v21, v0
	v_pk_fma_f32 v[34:35], v[32:33], v[28:29], v[30:31] op_sel_hi:[0,1,1] neg_lo:[0,0,1] neg_hi:[0,0,1]
	v_pk_fma_f32 v[30:31], v[32:33], v[28:29], v[30:31] op_sel_hi:[0,1,1]
	v_pk_mov_b32 v[38:39], v[30:31], v[34:35] op_sel:[1,0]
	v_mov_b32_e32 v36, v34
	v_mov_b32_e32 v37, v31
	v_pk_mul_f32 v[38:39], v[30:31], v[38:39] op_sel:[1,0]
	v_mul_f32_e32 v0, v25, v34
	v_pk_mul_f32 v[28:29], v[28:29], v[36:37]
	v_pk_fma_f32 v[44:45], v[34:35], v[36:37], v[38:39] op_sel_hi:[0,1,1] neg_lo:[0,0,1] neg_hi:[0,0,1]
	v_pk_fma_f32 v[36:37], v[34:35], v[36:37], v[38:39] op_sel_hi:[0,1,1]
	v_fmac_f32_e32 v0, v32, v31
	v_pk_mov_b32 v[38:39], v[36:37], v[44:45] op_sel:[1,0]
	v_sub_f32_e32 v16, v28, v29
	v_mov_b32_e32 v28, v44
	v_mov_b32_e32 v29, v37
	v_cndmask_b32_e32 v0, v0, v31, vcc
	v_pk_mul_f32 v[30:31], v[36:37], v[38:39] op_sel:[1,0]
	v_cndmask_b32_e64 v0, v0, v25, s[2:3]
	v_pk_fma_f32 v[46:47], v[44:45], v[28:29], v[30:31] op_sel_hi:[0,1,1] neg_lo:[0,0,1] neg_hi:[0,0,1]
	v_pk_fma_f32 v[52:53], v[44:45], v[28:29], v[30:31] op_sel_hi:[0,1,1]
	s_waitcnt vmcnt(13)
; __device__ __forceinline__ unsigned pk2(float lo, float hi) { f32x2 v = {lo, hi}; nbf2 r = __builtin_convertvector(v, nbf2); return __builtin_bit_cast(unsigned, r); }
; __device__ __forceinline__ bf16x4 cscale_bf(const bf16x4 re, const bf16x4 im, float wr, float wi, bool want_im) {
;     bf16x4 o;
; #pragma unroll
;     for (int k = 0; k < 4; k += 2) {
;         const float r0 = __uint_as_float((unsigned)(unsigned short)re[k] << 16), r1 = __uint_as_float((unsigned)(unsigned short)re[k + 1] << 16);
;         const float i0 = __uint_as_float((unsigned)(unsigned short)im[k] << 16), i1 = __uint_as_float((unsigned)(unsigned short)im[k + 1] << 16);
;         const unsigned w = want_im ? pk2(wr * i0 + wi * r0, wr * i1 + wi * r1) : pk2(wr * r0 - wi * i0, wr * r1 - wi * i1);
;         o[k] = (short)(w & 0xffffu); o[k + 1] = (short)(w >> 16);
;     }
;     return o;
; }
; template <int DIR>
; __device__ __forceinline__ void s5_local_dir(const bf16_t* UZ, unsigned char* ws, int gw, int NGW, int lane) {
;     ...
;     for (int t = 0; t < 4; ++t) {
;         const int p = 16 * t + fr;
;         const bf16x4 b_re = *(const bf16x4*)(Bb + (2 * p) * 16 + 4 * fq), b_im = *(const bf16x4*)(Bb + (2 * p + 1) * 16 + 4 * fq);
;         const f32x4 ap = ((const f32x4*)(ws + WS_APOW))[pair * 64 + p];
;         const float ar = ap.x, ai = ap.y;
;         float r2 = ar, i2 = ai; cmul(r2, i2, ar, ai);
;         float r4 = r2, i4 = i2; cmul(r4, i4, r2, i2);
;         float r8 = r4, i8 = i4; cmul(r8, i8, r4, i4);
;         float r12 = r8, i12 = i8; cmul(r12, i12, r4, i4);
;         float r16 = r8, i16 = i8; cmul(r16, i16, r8, i8);
;         float r32 = r16, i32 = i16; cmul(r32, i32, r16, i16);
;         float r48 = r32, i48 = i32; cmul(r48, i48, r16, i16);
;         a1r[t] = ar; a1i[t] = ai; a64r[t] = ap.z; a64i[t] = ap.w;
;         const int e = DIR ? fq : 3 - fq;
;         wr_[t] = e == 0 ? 1.f : e == 1 ? r4 : e == 2 ? r8 : r12; wi_[t] = e == 0 ? 0.f : e == 1 ? i4 : e == 2 ? i8 : i12;
; #pragma unroll
;         for (int m = 0; m < 4; ++m) {
;             const int em = DIR ? m : 3 - m;
;             const float pr = em == 0 ? 1.f : em == 1 ? r16 : em == 2 ? r32 : r48, pi = em == 0 ? 0.f : em == 1 ? i16 : em == 2 ? i32 : i48;
;             Bre[m][t] = cscale_bf(b_re, b_im, pr, pi, false); Bim[m][t] = cscale_bf(b_re, b_im, pr, pi, true);
;         }
	v_and_b32_e32 v43, 0xffff0000, v26
	v_lshlrev_b32_e32 v42, 16, v26
	v_cndmask_b32_e32 v16, v16, v34, vcc
	v_cndmask_b32_e64 v25, v0, 0, s[8:9]
	v_mov_b32_e32 v30, v46
	v_mov_b32_e32 v31, v53
	v_mul_f32_e32 v0, v37, v53
	v_and_b32_e32 v61, 0xffff0000, v27
	v_lshlrev_b32_e32 v60, 16, v27
	v_and_b32_e32 v41, 0xffff0000, v22
	v_lshlrev_b32_e32 v40, 16, v22
	v_cndmask_b32_e64 v16, v16, v32, s[2:3]
	v_pk_fma_f32 v[54:55], v[28:29], v[30:31], v[0:1] op_sel_hi:[1,1,0] neg_lo:[0,0,1] neg_hi:[0,0,1]
	v_and_b32_e32 v59, 0xffff0000, v23
	v_lshlrev_b32_e32 v58, 16, v23
	v_xor_b32_e32 v27, 0x80000000, v61
	v_xor_b32_e32 v26, 0x80000000, v60
	v_xor_b32_e32 v29, 0x80000000, v43
	v_xor_b32_e32 v28, 0x80000000, v42
	v_cndmask_b32_e64 v22, v16, 1.0, s[8:9]
	v_mul_f32_e32 v16, v44, v53
	v_pk_fma_f32 v[26:27], v[26:27], 0, v[58:59] op_sel_hi:[1,0,1]
	v_pk_fma_f32 v[28:29], v[28:29], 0, v[40:41] op_sel_hi:[1,0,1]
	v_pk_fma_f32 v[56:57], v[38:39], v[30:31], v[16:17] op_sel_hi:[1,1,0]
	v_cvt_pk_bf16_f32 v0, v28, s0
	v_cvt_pk_bf16_f32 v16, v29, s0
	v_cvt_pk_bf16_f32 v23, v26, s0
	v_cvt_pk_bf16_f32 v24, v27, s0
	v_pk_fma_f32 v[28:29], v[58:59], 0, v[60:61] op_sel_hi:[1,0,1]
	v_pk_fma_f32 v[30:31], v[40:41], 0, v[42:43] op_sel_hi:[1,0,1]
	v_pk_mul_f32 v[32:33], v[36:37], v[60:61] op_sel:[1,0]
	v_perm_b32 v27, v24, v23, s37
	v_perm_b32 v26, v16, v0, s37
	v_cvt_pk_bf16_f32 v0, v30, s0
	v_cvt_pk_bf16_f32 v16, v31, s0
	v_cvt_pk_bf16_f32 v23, v28, s0
	v_cvt_pk_bf16_f32 v24, v29, s0
	v_pk_mul_f32 v[30:31], v[36:37], v[42:43] op_sel:[1,0]
	v_pk_fma_f32 v[32:33], v[44:45], v[58:59], v[32:33] op_sel_hi:[0,1,1] neg_lo:[0,0,1] neg_hi:[0,0,1]
	v_pk_mul_f32 v[34:35], v[36:37], v[58:59] op_sel:[1,0]
	v_perm_b32 v29, v24, v23, s37
	v_pk_fma_f32 v[30:31], v[44:45], v[40:41], v[30:31] op_sel_hi:[0,1,1] neg_lo:[0,0,1] neg_hi:[0,0,1]
	v_cvt_pk_bf16_f32 v23, v32, s0
	v_cvt_pk_bf16_f32 v24, v33, s0
	v_pk_mul_f32 v[32:33], v[36:37], v[40:41] op_sel:[1,0]
	v_pk_fma_f32 v[34:35], v[44:45], v[60:61], v[34:35] op_sel_hi:[0,1,1]
	v_pk_mul_f32 v[36:37], v[52:53], v[60:61] op_sel:[1,0]
	v_perm_b32 v28, v16, v0, s37
	v_cvt_pk_bf16_f32 v0, v30, s0
	v_cvt_pk_bf16_f32 v16, v31, s0
	v_perm_b32 v31, v24, v23, s37
	v_pk_fma_f32 v[32:33], v[44:45], v[42:43], v[32:33] op_sel_hi:[0,1,1]
	v_cvt_pk_bf16_f32 v23, v34, s0
	v_cvt_pk_bf16_f32 v24, v35, s0
	v_pk_mul_f32 v[34:35], v[52:53], v[42:43] op_sel:[1,0]
	v_pk_fma_f32 v[36:37], v[46:47], v[58:59], v[36:37] op_sel_hi:[0,1,1] neg_lo:[0,0,1] neg_hi:[0,0,1]
	v_pk_mul_f32 v[38:39], v[52:53], v[58:59] op_sel:[1,0]
	v_perm_b32 v30, v16, v0, s37
	v_cvt_pk_bf16_f32 v0, v32, s0
	v_cvt_pk_bf16_f32 v16, v33, s0
	v_perm_b32 v33, v24, v23, s37
	v_pk_fma_f32 v[34:35], v[46:47], v[40:41], v[34:35] op_sel_hi:[0,1,1] neg_lo:[0,0,1] neg_hi:[0,0,1]
	v_cvt_pk_bf16_f32 v23, v36, s0
	v_cvt_pk_bf16_f32 v24, v37, s0
	v_pk_mul_f32 v[36:37], v[52:53], v[40:41] op_sel:[1,0]
	v_pk_fma_f32 v[38:39], v[46:47], v[60:61], v[38:39] op_sel_hi:[0,1,1]
	v_pk_mul_f32 v[44:45], v[56:57], v[60:61] op_sel_hi:[0,1]
	v_perm_b32 v32, v16, v0, s37
	v_cvt_pk_bf16_f32 v0, v34, s0
	v_cvt_pk_bf16_f32 v16, v35, s0
	v_perm_b32 v35, v24, v23, s37
	v_pk_fma_f32 v[36:37], v[46:47], v[42:43], v[36:37] op_sel_hi:[0,1,1]
	v_cvt_pk_bf16_f32 v23, v38, s0
	v_cvt_pk_bf16_f32 v24, v39, s0
	v_pk_fma_f32 v[44:45], v[54:55], v[58:59], v[44:45] op_sel_hi:[0,1,1] neg_lo:[0,0,1] neg_hi:[0,0,1]
	v_perm_b32 v34, v16, v0, s37
	v_cvt_pk_bf16_f32 v16, v37, s0
	v_perm_b32 v37, v24, v23, s37
	v_pk_mul_f32 v[38:39], v[56:57], v[42:43] op_sel_hi:[0,1]
	v_cvt_pk_bf16_f32 v23, v44, s0
	v_cvt_pk_bf16_f32 v24, v45, s0
	v_pk_mul_f32 v[44:45], v[56:57], v[58:59] op_sel_hi:[0,1]
	v_cvt_pk_bf16_f32 v0, v36, s0
	v_pk_fma_f32 v[38:39], v[54:55], v[40:41], v[38:39] op_sel_hi:[0,1,1] neg_lo:[0,0,1] neg_hi:[0,0,1]
	v_pk_fma_f32 v[44:45], v[54:55], v[60:61], v[44:45] op_sel_hi:[0,1,1]
	v_perm_b32 v36, v16, v0, s37
	v_cvt_pk_bf16_f32 v16, v39, s0
	v_perm_b32 v39, v24, v23, s37
	v_cvt_pk_bf16_f32 v23, v44, s0
	v_cvt_pk_bf16_f32 v24, v45, s0
	s_waitcnt vmcnt(10)
	v_pk_mul_f32 v[44:45], v[4:5], v[4:5] op_sel:[1,1] op_sel_hi:[1,0]
	v_pk_mul_f32 v[40:41], v[56:57], v[40:41] op_sel_hi:[0,1]
	v_pk_fma_f32 v[46:47], v[4:5], v[4:5], v[44:45] op_sel_hi:[1,0,1] neg_lo:[0,0,1] neg_hi:[0,0,1]
	v_pk_fma_f32 v[44:45], v[4:5], v[4:5], v[44:45] op_sel_hi:[1,0,1]
	v_pk_fma_f32 v[40:41], v[54:55], v[42:43], v[40:41] op_sel_hi:[0,1,1]
	v_pk_mov_b32 v[54:55], v[44:45], v[46:47] op_sel:[1,0]
	v_mov_b32_e32 v52, v46
	v_mov_b32_e32 v53, v45
	v_pk_mul_f32 v[44:45], v[44:45], v[54:55] op_sel:[1,0]
	v_cvt_pk_bf16_f32 v0, v38, s0
	v_pk_fma_f32 v[54:55], v[46:47], v[52:53], v[44:45] op_sel_hi:[0,1,1] neg_lo:[0,0,1] neg_hi:[0,0,1]
	v_pk_fma_f32 v[44:45], v[46:47], v[52:53], v[44:45] op_sel_hi:[0,1,1]
	v_pk_mov_b32 v[52:53], v[44:45], v[54:55] op_sel:[1,0]
	v_mov_b32_e32 v46, v54
	v_mov_b32_e32 v47, v45
	v_pk_mul_f32 v[52:53], v[44:45], v[52:53] op_sel:[1,0]
	v_perm_b32 v38, v16, v0, s37
	v_pk_fma_f32 v[56:57], v[54:55], v[46:47], v[52:53] op_sel_hi:[0,1,1] neg_lo:[0,0,1] neg_hi:[0,0,1]
	v_pk_fma_f32 v[52:53], v[54:55], v[46:47], v[52:53] op_sel_hi:[0,1,1]
	v_pk_mov_b32 v[60:61], v[52:53], v[56:57] op_sel:[1,0]
	v_mov_b32_e32 v58, v56
	v_mov_b32_e32 v59, v53
	v_pk_mul_f32 v[60:61], v[52:53], v[60:61] op_sel:[1,0]
	v_cvt_pk_bf16_f32 v0, v40, s0
	v_pk_fma_f32 v[62:63], v[56:57], v[58:59], v[60:61] op_sel_hi:[0,1,1] neg_lo:[0,0,1] neg_hi:[0,0,1]
	v_pk_fma_f32 v[60:61], v[56:57], v[58:59], v[60:61] op_sel_hi:[0,1,1]
	v_pk_mov_b32 v[66:67], v[60:61], v[62:63] op_sel:[1,0]
	v_mov_b32_e32 v64, v62
	v_mov_b32_e32 v65, v61
	v_pk_mul_f32 v[68:69], v[60:61], v[66:67] op_sel:[1,0]
; __device__ __forceinline__ unsigned pk2(float lo, float hi) { f32x2 v = {lo, hi}; nbf2 r = __builtin_convertvector(v, nbf2); return __builtin_bit_cast(unsigned, r); }
; __device__ __forceinline__ bf16x4 cscale_bf(const bf16x4 re, const bf16x4 im, float wr, float wi, bool want_im) {
;     bf16x4 o;
; #pragma unroll
;     for (int k = 0; k < 4; k += 2) {
;         const float r0 = __uint_as_float((unsigned)(unsigned short)re[k] << 16), r1 = __uint_as_float((unsigned)(unsigned short)re[k + 1] << 16);
;         const float i0 = __uint_as_float((unsigned)(unsigned short)im[k] << 16), i1 = __uint_as_float((unsigned)(unsigned short)im[k + 1] << 16);
;         const unsigned w = want_im ? pk2(wr * i0 + wi * r0, wr * i1 + wi * r1) : pk2(wr * r0 - wi * i0, wr * r1 - wi * i1);
;         o[k] = (short)(w & 0xffffu); o[k + 1] = (short)(w >> 16);
;     }
;     return o;
; }
; template <int DIR>
; __device__ __forceinline__ void s5_local_dir(const bf16_t* UZ, unsigned char* ws, int gw, int NGW, int lane) {
;     ...
;     for (int t = 0; t < 4; ++t) {
;         const int p = 16 * t + fr;
;         const bf16x4 b_re = *(const bf16x4*)(Bb + (2 * p) * 16 + 4 * fq), b_im = *(const bf16x4*)(Bb + (2 * p + 1) * 16 + 4 * fq);
;         const f32x4 ap = ((const f32x4*)(ws + WS_APOW))[pair * 64 + p];
;         const float ar = ap.x, ai = ap.y;
;         float r2 = ar, i2 = ai; cmul(r2, i2, ar, ai);
;         float r4 = r2, i4 = i2; cmul(r4, i4, r2, i2);
;         float r8 = r4, i8 = i4; cmul(r8, i8, r4, i4);
;         float r12 = r8, i12 = i8; cmul(r12, i12, r4, i4);
;         float r16 = r8, i16 = i8; cmul(r16, i16, r8, i8);
;         float r32 = r16, i32 = i16; cmul(r32, i32, r16, i16);
;         float r48 = r32, i48 = i32; cmul(r48, i48, r16, i16);
;         a1r[t] = ar; a1i[t] = ai; a64r[t] = ap.z; a64i[t] = ap.w;
;         const int e = DIR ? fq : 3 - fq;
;         wr_[t] = e == 0 ? 1.f : e == 1 ? r4 : e == 2 ? r8 : r12; wi_[t] = e == 0 ? 0.f : e == 1 ? i4 : e == 2 ? i8 : i12;
; #pragma unroll
;         for (int m = 0; m < 4; ++m) {
;             const int em = DIR ? m : 3 - m;
;             const float pr = em == 0 ? 1.f : em == 1 ? r16 : em == 2 ? r32 : r48, pi = em == 0 ? 0.f : em == 1 ? i16 : em == 2 ? i32 : i48;
;             Bre[m][t] = cscale_bf(b_re, b_im, pr, pi, false); Bim[m][t] = cscale_bf(b_re, b_im, pr, pi, true);
;         }
	v_cvt_pk_bf16_f32 v16, v41, s0
	v_pk_fma_f32 v[74:75], v[62:63], v[64:65], v[68:69] op_sel_hi:[0,1,1] neg_lo:[0,0,1] neg_hi:[0,0,1]
	v_pk_fma_f32 v[68:69], v[62:63], v[64:65], v[68:69] op_sel_hi:[0,1,1]
	v_perm_b32 v40, v16, v0, s37
	v_mov_b32_e32 v76, v74
	v_mov_b32_e32 v77, v69
	v_mul_f32_e32 v0, v61, v69
	v_pk_fma_f32 v[64:65], v[64:65], v[76:77], v[0:1] op_sel_hi:[1,1,0] neg_lo:[0,0,1] neg_hi:[0,0,1]
	v_mul_f32_e32 v0, v62, v69
	v_pk_fma_f32 v[66:67], v[66:67], v[76:77], v[0:1] op_sel_hi:[1,1,0]
	v_mul_f32_e32 v0, v45, v56
	v_pk_mul_f32 v[46:47], v[46:47], v[58:59]
	v_mov_b32_e32 v42, v4
	v_mov_b32_e32 v43, v4
	v_fmac_f32_e32 v0, v54, v53
	v_sub_f32_e32 v4, v46, v47
	v_and_b32_e32 v79, 0xffff0000, v48
	v_lshlrev_b32_e32 v78, 16, v48
	v_and_b32_e32 v83, 0xffff0000, v49
	v_lshlrev_b32_e32 v82, 16, v49
	v_cndmask_b32_e32 v4, v4, v56, vcc
	v_cndmask_b32_e32 v0, v0, v53, vcc
	v_and_b32_e32 v77, 0xffff0000, v50
	v_lshlrev_b32_e32 v76, 16, v50
	v_and_b32_e32 v81, 0xffff0000, v51
	v_lshlrev_b32_e32 v80, 16, v51
	v_xor_b32_e32 v49, 0x80000000, v83
	v_xor_b32_e32 v48, 0x80000000, v82
	v_xor_b32_e32 v51, 0x80000000, v79
	v_xor_b32_e32 v50, 0x80000000, v78
	v_cndmask_b32_e64 v4, v4, v54, s[2:3]
	v_cndmask_b32_e64 v0, v0, v45, s[2:3]
	v_pk_fma_f32 v[48:49], v[48:49], 0, v[80:81] op_sel_hi:[1,0,1]
	v_pk_fma_f32 v[50:51], v[50:51], 0, v[76:77] op_sel_hi:[1,0,1]
	v_perm_b32 v41, v24, v23, s37
	v_cndmask_b32_e64 v44, v4, 1.0, s[8:9]
	v_cndmask_b32_e64 v47, v0, 0, s[8:9]
	v_cvt_pk_bf16_f32 v0, v50, s0
	v_cvt_pk_bf16_f32 v4, v51, s0
	v_cvt_pk_bf16_f32 v16, v48, s0
	v_cvt_pk_bf16_f32 v23, v49, s0
	v_pk_fma_f32 v[50:51], v[80:81], 0, v[82:83] op_sel_hi:[1,0,1]
	v_pk_fma_f32 v[52:53], v[76:77], 0, v[78:79] op_sel_hi:[1,0,1]
	v_pk_mul_f32 v[54:55], v[60:61], v[82:83] op_sel:[1,0]
	v_perm_b32 v49, v23, v16, s37
	v_perm_b32 v48, v4, v0, s37
	v_cvt_pk_bf16_f32 v0, v52, s0
	v_cvt_pk_bf16_f32 v4, v53, s0
	v_cvt_pk_bf16_f32 v16, v50, s0
	v_cvt_pk_bf16_f32 v23, v51, s0
	v_pk_mul_f32 v[52:53], v[60:61], v[78:79] op_sel:[1,0]
	v_pk_fma_f32 v[54:55], v[62:63], v[80:81], v[54:55] op_sel_hi:[0,1,1] neg_lo:[0,0,1] neg_hi:[0,0,1]
	v_pk_mul_f32 v[56:57], v[60:61], v[80:81] op_sel:[1,0]
	v_perm_b32 v51, v23, v16, s37
	v_pk_fma_f32 v[52:53], v[62:63], v[76:77], v[52:53] op_sel_hi:[0,1,1] neg_lo:[0,0,1] neg_hi:[0,0,1]
	v_cvt_pk_bf16_f32 v16, v54, s0
	v_cvt_pk_bf16_f32 v23, v55, s0
	v_pk_mul_f32 v[54:55], v[60:61], v[76:77] op_sel:[1,0]
	v_pk_fma_f32 v[56:57], v[62:63], v[82:83], v[56:57] op_sel_hi:[0,1,1]
	v_pk_mul_f32 v[58:59], v[68:69], v[82:83] op_sel:[1,0]
	v_perm_b32 v50, v4, v0, s37
	v_cvt_pk_bf16_f32 v0, v52, s0
	v_cvt_pk_bf16_f32 v4, v53, s0
	v_perm_b32 v53, v23, v16, s37
	v_pk_fma_f32 v[54:55], v[62:63], v[78:79], v[54:55] op_sel_hi:[0,1,1]
	v_cvt_pk_bf16_f32 v16, v56, s0
	v_cvt_pk_bf16_f32 v23, v57, s0
	v_pk_mul_f32 v[56:57], v[68:69], v[78:79] op_sel:[1,0]
	v_pk_fma_f32 v[58:59], v[74:75], v[80:81], v[58:59] op_sel_hi:[0,1,1] neg_lo:[0,0,1] neg_hi:[0,0,1]
	v_pk_mul_f32 v[60:61], v[68:69], v[80:81] op_sel:[1,0]
	v_perm_b32 v52, v4, v0, s37
	v_cvt_pk_bf16_f32 v0, v54, s0
	v_cvt_pk_bf16_f32 v4, v55, s0
	v_perm_b32 v55, v23, v16, s37
	v_pk_fma_f32 v[56:57], v[74:75], v[76:77], v[56:57] op_sel_hi:[0,1,1] neg_lo:[0,0,1] neg_hi:[0,0,1]
	v_cvt_pk_bf16_f32 v16, v58, s0
	v_cvt_pk_bf16_f32 v23, v59, s0
	v_pk_mul_f32 v[58:59], v[68:69], v[76:77] op_sel:[1,0]
	v_pk_fma_f32 v[60:61], v[74:75], v[82:83], v[60:61] op_sel_hi:[0,1,1]
	v_pk_mul_f32 v[62:63], v[66:67], v[82:83] op_sel_hi:[0,1]
	v_perm_b32 v54, v4, v0, s37
	v_cvt_pk_bf16_f32 v0, v56, s0
	v_cvt_pk_bf16_f32 v4, v57, s0
	v_perm_b32 v57, v23, v16, s37
	v_pk_fma_f32 v[58:59], v[74:75], v[78:79], v[58:59] op_sel_hi:[0,1,1]
	v_cvt_pk_bf16_f32 v16, v60, s0
	v_cvt_pk_bf16_f32 v23, v61, s0
	v_pk_fma_f32 v[62:63], v[64:65], v[80:81], v[62:63] op_sel_hi:[0,1,1] neg_lo:[0,0,1] neg_hi:[0,0,1]
	v_perm_b32 v56, v4, v0, s37
	v_cvt_pk_bf16_f32 v4, v59, s0
	v_perm_b32 v59, v23, v16, s37
	v_pk_mul_f32 v[60:61], v[66:67], v[78:79] op_sel_hi:[0,1]
	v_cvt_pk_bf16_f32 v16, v62, s0
	v_cvt_pk_bf16_f32 v23, v63, s0
	v_pk_mul_f32 v[62:63], v[66:67], v[76:77] op_sel_hi:[0,1]
	v_pk_mul_f32 v[66:67], v[66:67], v[80:81] op_sel_hi:[0,1]
	v_cvt_pk_bf16_f32 v0, v58, s0
	v_pk_fma_f32 v[60:61], v[64:65], v[76:77], v[60:61] op_sel_hi:[0,1,1] neg_lo:[0,0,1] neg_hi:[0,0,1]
	v_pk_fma_f32 v[66:67], v[64:65], v[82:83], v[66:67] op_sel_hi:[0,1,1]
	v_perm_b32 v58, v4, v0, s37
	v_cvt_pk_bf16_f32 v4, v61, s0
	v_perm_b32 v61, v23, v16, s37
	v_cvt_pk_bf16_f32 v16, v66, s0
	v_cvt_pk_bf16_f32 v23, v67, s0
	s_waitcnt vmcnt(7)
; __device__ __forceinline__ unsigned pk2(float lo, float hi) { f32x2 v = {lo, hi}; nbf2 r = __builtin_convertvector(v, nbf2); return __builtin_bit_cast(unsigned, r); }
; __device__ __forceinline__ bf16x4 cscale_bf(const bf16x4 re, const bf16x4 im, float wr, float wi, bool want_im) {
;     bf16x4 o;
; #pragma unroll
;     for (int k = 0; k < 4; k += 2) {
;         const float r0 = __uint_as_float((unsigned)(unsigned short)re[k] << 16), r1 = __uint_as_float((unsigned)(unsigned short)re[k + 1] << 16);
;         const float i0 = __uint_as_float((unsigned)(unsigned short)im[k] << 16), i1 = __uint_as_float((unsigned)(unsigned short)im[k + 1] << 16);
;         const unsigned w = want_im ? pk2(wr * i0 + wi * r0, wr * i1 + wi * r1) : pk2(wr * r0 - wi * i0, wr * r1 - wi * i1);
;         o[k] = (short)(w & 0xffffu); o[k + 1] = (short)(w >> 16);
;     }
;     return o;
; }
; template <int DIR>
; __device__ __forceinline__ void s5_local_dir(const bf16_t* UZ, unsigned char* ws, int gw, int NGW, int lane) {
;     ...
;     for (int t = 0; t < 4; ++t) {
;         const int p = 16 * t + fr;
;         const bf16x4 b_re = *(const bf16x4*)(Bb + (2 * p) * 16 + 4 * fq), b_im = *(const bf16x4*)(Bb + (2 * p + 1) * 16 + 4 * fq);
;         const f32x4 ap = ((const f32x4*)(ws + WS_APOW))[pair * 64 + p];
;         const float ar = ap.x, ai = ap.y;
;         float r2 = ar, i2 = ai; cmul(r2, i2, ar, ai);
;         float r4 = r2, i4 = i2; cmul(r4, i4, r2, i2);
;         float r8 = r4, i8 = i4; cmul(r8, i8, r4, i4);
;         float r12 = r8, i12 = i8; cmul(r12, i12, r4, i4);
;         float r16 = r8, i16 = i8; cmul(r16, i16, r8, i8);
;         float r32 = r16, i32 = i16; cmul(r32, i32, r16, i16);
;         float r48 = r32, i48 = i32; cmul(r48, i48, r16, i16);
;         a1r[t] = ar; a1i[t] = ai; a64r[t] = ap.z; a64i[t] = ap.w;
;         const int e = DIR ? fq : 3 - fq;
;         wr_[t] = e == 0 ? 1.f : e == 1 ? r4 : e == 2 ? r8 : r12; wi_[t] = e == 0 ? 0.f : e == 1 ? i4 : e == 2 ? i8 : i12;
; #pragma unroll
;         for (int m = 0; m < 4; ++m) {
;             const int em = DIR ? m : 3 - m;
;             const float pr = em == 0 ? 1.f : em == 1 ? r16 : em == 2 ? r32 : r48, pi = em == 0 ? 0.f : em == 1 ? i16 : em == 2 ? i32 : i48;
;             Bre[m][t] = cscale_bf(b_re, b_im, pr, pi, false); Bim[m][t] = cscale_bf(b_re, b_im, pr, pi, true);
;         }
	v_pk_mul_f32 v[66:67], v[8:9], v[8:9] op_sel:[1,1] op_sel_hi:[1,0]
	v_pk_fma_f32 v[62:63], v[64:65], v[78:79], v[62:63] op_sel_hi:[0,1,1]
	v_pk_fma_f32 v[68:69], v[8:9], v[8:9], v[66:67] op_sel_hi:[1,0,1] neg_lo:[0,0,1] neg_hi:[0,0,1]
	v_pk_fma_f32 v[66:67], v[8:9], v[8:9], v[66:67] op_sel_hi:[1,0,1]
	v_mov_b32_e32 v74, v68
	v_pk_mov_b32 v[76:77], v[66:67], v[68:69] op_sel:[1,0]
	v_mov_b32_e32 v75, v67
	v_pk_mul_f32 v[66:67], v[66:67], v[76:77] op_sel:[1,0]
	v_cvt_pk_bf16_f32 v0, v60, s0
	v_pk_fma_f32 v[76:77], v[68:69], v[74:75], v[66:67] op_sel_hi:[0,1,1] neg_lo:[0,0,1] neg_hi:[0,0,1]
	v_pk_fma_f32 v[66:67], v[68:69], v[74:75], v[66:67] op_sel_hi:[0,1,1]
	v_pk_mov_b32 v[74:75], v[66:67], v[76:77] op_sel:[1,0]
	v_mov_b32_e32 v68, v76
	v_mov_b32_e32 v69, v67
	v_pk_mul_f32 v[74:75], v[66:67], v[74:75] op_sel:[1,0]
	v_perm_b32 v60, v4, v0, s37
	v_pk_fma_f32 v[78:79], v[76:77], v[68:69], v[74:75] op_sel_hi:[0,1,1] neg_lo:[0,0,1] neg_hi:[0,0,1]
	v_pk_fma_f32 v[74:75], v[76:77], v[68:69], v[74:75] op_sel_hi:[0,1,1]
	v_pk_mov_b32 v[82:83], v[74:75], v[78:79] op_sel:[1,0]
	v_mov_b32_e32 v80, v78
	v_mov_b32_e32 v81, v75
	v_pk_mul_f32 v[82:83], v[74:75], v[82:83] op_sel:[1,0]
	v_cvt_pk_bf16_f32 v0, v62, s0
	v_pk_fma_f32 v[84:85], v[78:79], v[80:81], v[82:83] op_sel_hi:[0,1,1] neg_lo:[0,0,1] neg_hi:[0,0,1]
	v_pk_fma_f32 v[82:83], v[78:79], v[80:81], v[82:83] op_sel_hi:[0,1,1]
	v_pk_mov_b32 v[88:89], v[82:83], v[84:85] op_sel:[1,0]
	v_mov_b32_e32 v86, v84
	v_mov_b32_e32 v87, v83
	v_pk_mul_f32 v[90:91], v[82:83], v[88:89] op_sel:[1,0]
	v_cvt_pk_bf16_f32 v4, v63, s0
	v_pk_fma_f32 v[96:97], v[84:85], v[86:87], v[90:91] op_sel_hi:[0,1,1] neg_lo:[0,0,1] neg_hi:[0,0,1]
	v_pk_fma_f32 v[90:91], v[84:85], v[86:87], v[90:91] op_sel_hi:[0,1,1]
	v_perm_b32 v62, v4, v0, s37
	v_mov_b32_e32 v98, v96
	v_mov_b32_e32 v99, v91
	v_mul_f32_e32 v0, v83, v91
	v_pk_fma_f32 v[86:87], v[86:87], v[98:99], v[0:1] op_sel_hi:[1,1,0] neg_lo:[0,0,1] neg_hi:[0,0,1]
	v_mul_f32_e32 v0, v84, v91
	v_pk_fma_f32 v[88:89], v[88:89], v[98:99], v[0:1] op_sel_hi:[1,1,0]
	v_mul_f32_e32 v0, v67, v78
	v_pk_mul_f32 v[68:69], v[68:69], v[80:81]
	v_fmac_f32_e32 v0, v76, v75
	v_sub_f32_e32 v4, v68, v69
	v_and_b32_e32 v101, 0xffff0000, v70
	v_lshlrev_b32_e32 v100, 16, v70
	v_and_b32_e32 v105, 0xffff0000, v71
	v_lshlrev_b32_e32 v104, 16, v71
	v_cndmask_b32_e32 v4, v4, v78, vcc
	v_cndmask_b32_e32 v0, v0, v75, vcc
	v_and_b32_e32 v99, 0xffff0000, v72
	v_lshlrev_b32_e32 v98, 16, v72
	v_and_b32_e32 v103, 0xffff0000, v73
	v_lshlrev_b32_e32 v102, 16, v73
	v_xor_b32_e32 v71, 0x80000000, v105
	v_xor_b32_e32 v70, 0x80000000, v104
	v_xor_b32_e32 v73, 0x80000000, v101
	v_xor_b32_e32 v72, 0x80000000, v100
	v_cndmask_b32_e64 v4, v4, v76, s[2:3]
	v_cndmask_b32_e64 v0, v0, v67, s[2:3]
	v_pk_fma_f32 v[70:71], v[70:71], 0, v[102:103] op_sel_hi:[1,0,1]
	v_pk_fma_f32 v[72:73], v[72:73], 0, v[98:99] op_sel_hi:[1,0,1]
	v_perm_b32 v63, v23, v16, s37
	v_mov_b32_e32 v64, v8
	v_mov_b32_e32 v65, v8
	v_cndmask_b32_e64 v66, v4, 1.0, s[8:9]
	v_cndmask_b32_e64 v69, v0, 0, s[8:9]
	v_cvt_pk_bf16_f32 v0, v72, s0
	v_cvt_pk_bf16_f32 v4, v73, s0
	v_cvt_pk_bf16_f32 v8, v70, s0
	v_cvt_pk_bf16_f32 v16, v71, s0
	v_pk_fma_f32 v[72:73], v[102:103], 0, v[104:105] op_sel_hi:[1,0,1]
	v_pk_fma_f32 v[74:75], v[98:99], 0, v[100:101] op_sel_hi:[1,0,1]
	v_pk_mul_f32 v[76:77], v[82:83], v[104:105] op_sel:[1,0]
	v_perm_b32 v71, v16, v8, s37
	v_perm_b32 v70, v4, v0, s37
	v_cvt_pk_bf16_f32 v0, v74, s0
	v_cvt_pk_bf16_f32 v4, v75, s0
	v_cvt_pk_bf16_f32 v8, v72, s0
	v_cvt_pk_bf16_f32 v16, v73, s0
	v_pk_mul_f32 v[74:75], v[82:83], v[100:101] op_sel:[1,0]
	v_pk_fma_f32 v[76:77], v[84:85], v[102:103], v[76:77] op_sel_hi:[0,1,1] neg_lo:[0,0,1] neg_hi:[0,0,1]
	v_pk_mul_f32 v[78:79], v[82:83], v[102:103] op_sel:[1,0]
	v_perm_b32 v73, v16, v8, s37
	v_pk_fma_f32 v[74:75], v[84:85], v[98:99], v[74:75] op_sel_hi:[0,1,1] neg_lo:[0,0,1] neg_hi:[0,0,1]
	v_cvt_pk_bf16_f32 v8, v76, s0
	v_cvt_pk_bf16_f32 v16, v77, s0
	v_pk_mul_f32 v[76:77], v[82:83], v[98:99] op_sel:[1,0]
	v_pk_fma_f32 v[78:79], v[84:85], v[104:105], v[78:79] op_sel_hi:[0,1,1]
	v_pk_mul_f32 v[80:81], v[90:91], v[104:105] op_sel:[1,0]
	v_perm_b32 v72, v4, v0, s37
	v_cvt_pk_bf16_f32 v0, v74, s0
	v_cvt_pk_bf16_f32 v4, v75, s0
	v_perm_b32 v75, v16, v8, s37
	v_pk_fma_f32 v[76:77], v[84:85], v[100:101], v[76:77] op_sel_hi:[0,1,1]
	v_cvt_pk_bf16_f32 v8, v78, s0
	v_cvt_pk_bf16_f32 v16, v79, s0
	v_pk_mul_f32 v[78:79], v[90:91], v[100:101] op_sel:[1,0]
	v_pk_fma_f32 v[80:81], v[96:97], v[102:103], v[80:81] op_sel_hi:[0,1,1] neg_lo:[0,0,1] neg_hi:[0,0,1]
	v_pk_mul_f32 v[82:83], v[90:91], v[102:103] op_sel:[1,0]
	v_perm_b32 v74, v4, v0, s37
	v_cvt_pk_bf16_f32 v0, v76, s0
	v_cvt_pk_bf16_f32 v4, v77, s0
	v_perm_b32 v77, v16, v8, s37
	v_pk_fma_f32 v[78:79], v[96:97], v[98:99], v[78:79] op_sel_hi:[0,1,1] neg_lo:[0,0,1] neg_hi:[0,0,1]
	v_cvt_pk_bf16_f32 v8, v80, s0
	v_cvt_pk_bf16_f32 v16, v81, s0
	v_pk_mul_f32 v[80:81], v[90:91], v[98:99] op_sel:[1,0]
	v_pk_fma_f32 v[82:83], v[96:97], v[104:105], v[82:83] op_sel_hi:[0,1,1]
	v_pk_mul_f32 v[84:85], v[88:89], v[104:105] op_sel_hi:[0,1]
	v_perm_b32 v76, v4, v0, s37
	v_cvt_pk_bf16_f32 v0, v78, s0
	v_cvt_pk_bf16_f32 v4, v79, s0
	v_perm_b32 v79, v16, v8, s37
	v_pk_fma_f32 v[80:81], v[96:97], v[100:101], v[80:81] op_sel_hi:[0,1,1]
	v_cvt_pk_bf16_f32 v8, v82, s0
	v_cvt_pk_bf16_f32 v16, v83, s0
	v_pk_fma_f32 v[84:85], v[86:87], v[102:103], v[84:85] op_sel_hi:[0,1,1] neg_lo:[0,0,1] neg_hi:[0,0,1]
	v_perm_b32 v78, v4, v0, s37
	v_cvt_pk_bf16_f32 v4, v81, s0
	v_perm_b32 v81, v16, v8, s37
	v_pk_mul_f32 v[82:83], v[88:89], v[100:101] op_sel_hi:[0,1]
	v_cvt_pk_bf16_f32 v8, v84, s0
	v_cvt_pk_bf16_f32 v16, v85, s0
	v_pk_mul_f32 v[84:85], v[88:89], v[98:99] op_sel_hi:[0,1]
	v_pk_mul_f32 v[88:89], v[88:89], v[102:103] op_sel_hi:[0,1]
	v_cvt_pk_bf16_f32 v0, v80, s0
	v_pk_fma_f32 v[82:83], v[86:87], v[98:99], v[82:83] op_sel_hi:[0,1,1] neg_lo:[0,0,1] neg_hi:[0,0,1]
	v_pk_fma_f32 v[88:89], v[86:87], v[104:105], v[88:89] op_sel_hi:[0,1,1]
	v_perm_b32 v80, v4, v0, s37
	v_cvt_pk_bf16_f32 v4, v83, s0
	v_perm_b32 v83, v16, v8, s37
	v_cvt_pk_bf16_f32 v8, v88, s0
	v_cvt_pk_bf16_f32 v16, v89, s0
	s_waitcnt vmcnt(4)
; __device__ __forceinline__ unsigned pk2(float lo, float hi) { f32x2 v = {lo, hi}; nbf2 r = __builtin_convertvector(v, nbf2); return __builtin_bit_cast(unsigned, r); }
; __device__ __forceinline__ bf16x4 cscale_bf(const bf16x4 re, const bf16x4 im, float wr, float wi, bool want_im) {
;     bf16x4 o;
; #pragma unroll
;     for (int k = 0; k < 4; k += 2) {
;         const float r0 = __uint_as_float((unsigned)(unsigned short)re[k] << 16), r1 = __uint_as_float((unsigned)(unsigned short)re[k + 1] << 16);
;         const float i0 = __uint_as_float((unsigned)(unsigned short)im[k] << 16), i1 = __uint_as_float((unsigned)(unsigned short)im[k + 1] << 16);
;         const unsigned w = want_im ? pk2(wr * i0 + wi * r0, wr * i1 + wi * r1) : pk2(wr * r0 - wi * i0, wr * r1 - wi * i1);
;         o[k] = (short)(w & 0xffffu); o[k + 1] = (short)(w >> 16);
;     }
;     return o;
; }
; template <int DIR>
; __device__ __forceinline__ void s5_local_dir(const bf16_t* UZ, unsigned char* ws, int gw, int NGW, int lane) {
;     ...
;     for (int t = 0; t < 4; ++t) {
;         const int p = 16 * t + fr;
;         const bf16x4 b_re = *(const bf16x4*)(Bb + (2 * p) * 16 + 4 * fq), b_im = *(const bf16x4*)(Bb + (2 * p + 1) * 16 + 4 * fq);
;         const f32x4 ap = ((const f32x4*)(ws + WS_APOW))[pair * 64 + p];
;         const float ar = ap.x, ai = ap.y;
;         float r2 = ar, i2 = ai; cmul(r2, i2, ar, ai);
;         float r4 = r2, i4 = i2; cmul(r4, i4, r2, i2);
;         float r8 = r4, i8 = i4; cmul(r8, i8, r4, i4);
;         float r12 = r8, i12 = i8; cmul(r12, i12, r4, i4);
;         float r16 = r8, i16 = i8; cmul(r16, i16, r8, i8);
;         float r32 = r16, i32 = i16; cmul(r32, i32, r16, i16);
;         float r48 = r32, i48 = i32; cmul(r48, i48, r16, i16);
;         a1r[t] = ar; a1i[t] = ai; a64r[t] = ap.z; a64i[t] = ap.w;
;         const int e = DIR ? fq : 3 - fq;
;         wr_[t] = e == 0 ? 1.f : e == 1 ? r4 : e == 2 ? r8 : r12; wi_[t] = e == 0 ? 0.f : e == 1 ? i4 : e == 2 ? i8 : i12;
; #pragma unroll
;         for (int m = 0; m < 4; ++m) {
;             const int em = DIR ? m : 3 - m;
;             const float pr = em == 0 ? 1.f : em == 1 ? r16 : em == 2 ? r32 : r48, pi = em == 0 ? 0.f : em == 1 ? i16 : em == 2 ? i32 : i48;
;             Bre[m][t] = cscale_bf(b_re, b_im, pr, pi, false); Bim[m][t] = cscale_bf(b_re, b_im, pr, pi, true);
;         }
	v_pk_mul_f32 v[88:89], v[12:13], v[12:13] op_sel:[1,1] op_sel_hi:[1,0]
	v_pk_fma_f32 v[84:85], v[86:87], v[100:101], v[84:85] op_sel_hi:[0,1,1]
	v_pk_fma_f32 v[90:91], v[12:13], v[12:13], v[88:89] op_sel_hi:[1,0,1] neg_lo:[0,0,1] neg_hi:[0,0,1]
	v_pk_fma_f32 v[88:89], v[12:13], v[12:13], v[88:89] op_sel_hi:[1,0,1]
	v_mov_b32_e32 v96, v90
	v_pk_mov_b32 v[98:99], v[88:89], v[90:91] op_sel:[1,0]
	v_mov_b32_e32 v97, v89
	v_pk_mul_f32 v[88:89], v[88:89], v[98:99] op_sel:[1,0]
	v_cvt_pk_bf16_f32 v0, v82, s0
	v_pk_fma_f32 v[98:99], v[90:91], v[96:97], v[88:89] op_sel_hi:[0,1,1] neg_lo:[0,0,1] neg_hi:[0,0,1]
	v_pk_fma_f32 v[88:89], v[90:91], v[96:97], v[88:89] op_sel_hi:[0,1,1]
	v_pk_mov_b32 v[96:97], v[88:89], v[98:99] op_sel:[1,0]
	v_mov_b32_e32 v90, v98
	v_mov_b32_e32 v91, v89
	v_pk_mul_f32 v[96:97], v[88:89], v[96:97] op_sel:[1,0]
	v_perm_b32 v82, v4, v0, s37
	v_pk_fma_f32 v[100:101], v[98:99], v[90:91], v[96:97] op_sel_hi:[0,1,1] neg_lo:[0,0,1] neg_hi:[0,0,1]
	v_pk_fma_f32 v[96:97], v[98:99], v[90:91], v[96:97] op_sel_hi:[0,1,1]
	v_pk_mov_b32 v[104:105], v[96:97], v[100:101] op_sel:[1,0]
	v_mov_b32_e32 v102, v100
	v_mov_b32_e32 v103, v97
	v_pk_mul_f32 v[104:105], v[96:97], v[104:105] op_sel:[1,0]
	v_cvt_pk_bf16_f32 v0, v84, s0
	v_pk_fma_f32 v[106:107], v[100:101], v[102:103], v[104:105] op_sel_hi:[0,1,1] neg_lo:[0,0,1] neg_hi:[0,0,1]
	v_pk_fma_f32 v[104:105], v[100:101], v[102:103], v[104:105] op_sel_hi:[0,1,1]
	v_pk_mov_b32 v[110:111], v[104:105], v[106:107] op_sel:[1,0]
	v_mov_b32_e32 v108, v106
	v_mov_b32_e32 v109, v105
	v_pk_mul_f32 v[112:113], v[104:105], v[110:111] op_sel:[1,0]
	v_cvt_pk_bf16_f32 v4, v85, s0
	v_pk_fma_f32 v[116:117], v[106:107], v[108:109], v[112:113] op_sel_hi:[0,1,1] neg_lo:[0,0,1] neg_hi:[0,0,1]
	v_pk_fma_f32 v[112:113], v[106:107], v[108:109], v[112:113] op_sel_hi:[0,1,1]
	v_perm_b32 v84, v4, v0, s37
	v_mov_b32_e32 v114, v116
	v_mov_b32_e32 v115, v113
	v_mul_f32_e32 v0, v105, v113
	v_pk_fma_f32 v[118:119], v[108:109], v[114:115], v[0:1] op_sel_hi:[1,1,0] neg_lo:[0,0,1] neg_hi:[0,0,1]
	v_mul_f32_e32 v0, v106, v113
	v_pk_fma_f32 v[120:121], v[110:111], v[114:115], v[0:1] op_sel_hi:[1,1,0]
	v_mul_f32_e32 v0, v89, v100
	v_pk_mul_f32 v[90:91], v[90:91], v[102:103]
	v_fmac_f32_e32 v0, v98, v97
	v_sub_f32_e32 v4, v90, v91
	v_and_b32_e32 v125, 0xffff0000, v92
	v_lshlrev_b32_e32 v124, 16, v92
	v_and_b32_e32 v135, 0xffff0000, v93
	v_lshlrev_b32_e32 v134, 16, v93
	v_cndmask_b32_e32 v4, v4, v100, vcc
	v_cndmask_b32_e32 v0, v0, v97, vcc
	v_and_b32_e32 v123, 0xffff0000, v94
	v_lshlrev_b32_e32 v122, 16, v94
	v_and_b32_e32 v133, 0xffff0000, v95
	v_lshlrev_b32_e32 v132, 16, v95
	v_xor_b32_e32 v93, 0x80000000, v135
	v_xor_b32_e32 v92, 0x80000000, v134
	v_xor_b32_e32 v95, 0x80000000, v125
	v_xor_b32_e32 v94, 0x80000000, v124
	v_cndmask_b32_e64 v4, v4, v98, s[2:3]
	v_cndmask_b32_e64 v0, v0, v89, s[2:3]
	v_pk_fma_f32 v[92:93], v[92:93], 0, v[132:133] op_sel_hi:[1,0,1]
	v_pk_fma_f32 v[94:95], v[94:95], 0, v[122:123] op_sel_hi:[1,0,1]
	v_perm_b32 v85, v16, v8, s37
	v_mov_b32_e32 v86, v12
	v_mov_b32_e32 v87, v12
	v_cndmask_b32_e64 v88, v4, 1.0, s[8:9]
	v_cndmask_b32_e64 v91, v0, 0, s[8:9]
	v_cvt_pk_bf16_f32 v0, v94, s0
	v_cvt_pk_bf16_f32 v4, v95, s0
	v_cvt_pk_bf16_f32 v8, v92, s0
	v_cvt_pk_bf16_f32 v12, v93, s0
	v_pk_fma_f32 v[94:95], v[132:133], 0, v[134:135] op_sel_hi:[1,0,1]
	v_pk_fma_f32 v[96:97], v[122:123], 0, v[124:125] op_sel_hi:[1,0,1]
	v_pk_mul_f32 v[98:99], v[104:105], v[134:135] op_sel:[1,0]
	v_perm_b32 v93, v12, v8, s37
	v_perm_b32 v92, v4, v0, s37
	v_cvt_pk_bf16_f32 v0, v96, s0
	v_cvt_pk_bf16_f32 v4, v97, s0
	v_cvt_pk_bf16_f32 v8, v94, s0
	v_cvt_pk_bf16_f32 v12, v95, s0
	v_pk_mul_f32 v[96:97], v[104:105], v[124:125] op_sel:[1,0]
	v_pk_fma_f32 v[98:99], v[106:107], v[132:133], v[98:99] op_sel_hi:[0,1,1] neg_lo:[0,0,1] neg_hi:[0,0,1]
	v_pk_mul_f32 v[100:101], v[104:105], v[132:133] op_sel:[1,0]
	v_perm_b32 v95, v12, v8, s37
	v_pk_fma_f32 v[96:97], v[106:107], v[122:123], v[96:97] op_sel_hi:[0,1,1] neg_lo:[0,0,1] neg_hi:[0,0,1]
	v_cvt_pk_bf16_f32 v8, v98, s0
	v_cvt_pk_bf16_f32 v12, v99, s0
	v_pk_mul_f32 v[98:99], v[104:105], v[122:123] op_sel:[1,0]
	v_pk_fma_f32 v[100:101], v[106:107], v[134:135], v[100:101] op_sel_hi:[0,1,1]
	v_perm_b32 v94, v4, v0, s37
	v_cvt_pk_bf16_f32 v0, v96, s0
	v_cvt_pk_bf16_f32 v4, v97, s0
	v_perm_b32 v97, v12, v8, s37
	v_pk_fma_f32 v[98:99], v[106:107], v[124:125], v[98:99] op_sel_hi:[0,1,1]
	v_cvt_pk_bf16_f32 v8, v100, s0
	v_cvt_pk_bf16_f32 v12, v101, s0
	v_pk_mul_f32 v[100:101], v[112:113], v[124:125] op_sel:[1,0]
	v_perm_b32 v96, v4, v0, s37
	v_cvt_pk_bf16_f32 v0, v98, s0
	v_cvt_pk_bf16_f32 v4, v99, s0
	v_pk_fma_f32 v[100:101], v[116:117], v[122:123], v[100:101] op_sel_hi:[0,1,1] neg_lo:[0,0,1] neg_hi:[0,0,1]
	v_perm_b32 v98, v4, v0, s37
	v_cvt_pk_bf16_f32 v0, v100, s0
	v_cvt_pk_bf16_f32 v4, v101, s0
	s_mul_i32 s2, s43, 0xfffffbc0
	v_perm_b32 v100, v4, v0, s37
	v_or_b32_e32 v0, s2, v127
	s_cselect_b32 s2, s47, s48
	v_add_u32_e32 v106, s2, v0
	v_or_b32_e32 v110, 16, v106
	v_ashrrev_i32_e32 v111, 31, v110
	v_ashrrev_i32_e32 v107, 31, v106
	v_lshlrev_b64 v[110:111], 12, v[110:111]
	v_lshlrev_b64 v[108:109], 12, v[106:107]
	v_lshl_add_u64 v[136:137], v[18:19], 0, v[110:111]
	v_or_b32_e32 v110, 32, v106
	v_or_b32_e32 v106, 48, v106
	v_pk_mul_f32 v[102:103], v[112:113], v[134:135] op_sel:[1,0]
	v_ashrrev_i32_e32 v111, 31, v110
	v_ashrrev_i32_e32 v107, 31, v106
	v_pk_fma_f32 v[102:103], v[116:117], v[132:133], v[102:103] op_sel_hi:[0,1,1] neg_lo:[0,0,1] neg_hi:[0,0,1]
	v_lshl_add_u64 v[108:109], v[18:19], 0, v[108:109]
	v_lshlrev_b64 v[110:111], 12, v[110:111]
	v_lshlrev_b64 v[106:107], 12, v[106:107]
	v_perm_b32 v99, v12, v8, s37
	v_cvt_pk_bf16_f32 v8, v102, s0
	v_cvt_pk_bf16_f32 v12, v103, s0
	v_pk_mul_f32 v[102:103], v[112:113], v[122:123] op_sel:[1,0]
	v_pk_mul_f32 v[104:105], v[112:113], v[132:133] op_sel:[1,0]
	v_lshl_add_u64 v[138:139], v[18:19], 0, v[110:111]
	v_lshl_add_u64 v[106:107], v[18:19], 0, v[106:107]
	s_waitcnt vmcnt(0)
; template <int DIR>
; __device__ __forceinline__ void s5_local_dir(const bf16_t* UZ, unsigned char* ws, int gw, int NGW, int lane) {
;     ...
;         a1r[t] = ar; a1i[t] = ai; a64r[t] = ap.z; a64i[t] = ap.w;
;         const int e = DIR ? fq : 3 - fq;
;         wr_[t] = e == 0 ? 1.f : e == 1 ? r4 : e == 2 ? r8 : r12; wi_[t] = e == 0 ? 0.f : e == 1 ? i4 : e == 2 ? i8 : i12;
; #pragma unroll
;         for (int m = 0; m < 4; ++m) {
;             const int em = DIR ? m : 3 - m;
;             const float pr = em == 0 ? 1.f : em == 1 ? r16 : em == 2 ? r32 : r48, pi = em == 0 ? 0.f : em == 1 ? i16 : em == 2 ? i32 : i48;
;             Bre[m][t] = cscale_bf(b_re, b_im, pr, pi, false); Bim[m][t] = cscale_bf(b_re, b_im, pr, pi, true);
;         }
;     }
;     const int qd = gw >> 7, b = qd >> 2, q = qd & 3;
;     if (qd >= 16) return;
;     const int c0 = 17 * q, c1 = q < 3 ? c0 + 17 : 67;
;     float Rr[4] = {0.f, 0.f, 0.f, 0.f}, Ri[4] = {0.f, 0.f, 0.f, 0.f};
;     float* ebase = E + ((size_t)((b * 2 + DIR) * 64 + g) * NCHUNK) * 128;
;     bf16x4 Un[4];
;     load_uf(Un, UZ, chunk_rowbase(b, DIR, c0), g, lane);
;     for (int c = c0; c < c1; ++c) {
;         bf16x4 Uf[4];
; #pragma unroll
;         for (int m = 0; m < 4; ++m) Uf[m] = Un[m];
;         if (c + 1 < c1) load_uf(Un, UZ, chunk_rowbase(b, DIR, c + 1), g, lane);
;         float* e = ebase + (size_t)c * 128;
	v_mov_b64_e32 v[110:111], v[152:153]
	v_mov_b64_e32 v[112:113], v[154:155]
	v_mov_b64_e32 v[114:115], v[156:157]
	v_mov_b64_e32 v[108:109], v[158:159]
	v_pk_fma_f32 v[104:105], v[116:117], v[134:135], v[104:105] op_sel_hi:[0,1,1]
	v_pk_mul_f32 v[106:107], v[120:121], v[134:135] op_sel_hi:[0,1]
	v_perm_b32 v101, v12, v8, s37
	v_pk_fma_f32 v[102:103], v[116:117], v[124:125], v[102:103] op_sel_hi:[0,1,1]
	v_cvt_pk_bf16_f32 v8, v104, s0
	v_cvt_pk_bf16_f32 v12, v105, s0
	v_pk_mul_f32 v[104:105], v[120:121], v[124:125] op_sel_hi:[0,1]
	v_pk_fma_f32 v[106:107], v[118:119], v[132:133], v[106:107] op_sel_hi:[0,1,1] neg_lo:[0,0,1] neg_hi:[0,0,1]
	v_cvt_pk_bf16_f32 v0, v102, s0
	v_cvt_pk_bf16_f32 v4, v103, s0
	v_perm_b32 v103, v12, v8, s37
	v_pk_fma_f32 v[104:105], v[118:119], v[122:123], v[104:105] op_sel_hi:[0,1,1] neg_lo:[0,0,1] neg_hi:[0,0,1]
	v_cvt_pk_bf16_f32 v8, v106, s0
	v_cvt_pk_bf16_f32 v12, v107, s0
	v_pk_mul_f32 v[106:107], v[120:121], v[122:123] op_sel_hi:[0,1]
	v_perm_b32 v102, v4, v0, s37
	v_cvt_pk_bf16_f32 v0, v104, s0
	v_cvt_pk_bf16_f32 v4, v105, s0
	v_pk_fma_f32 v[106:107], v[118:119], v[124:125], v[106:107] op_sel_hi:[0,1,1]
	v_perm_b32 v104, v4, v0, s37
	v_pk_mul_f32 v[116:117], v[120:121], v[132:133] op_sel_hi:[0,1]
	v_cvt_pk_bf16_f32 v0, v106, s0
	v_cvt_pk_bf16_f32 v4, v107, s0
	s_add_i32 s2, s45, s44
	v_pk_fma_f32 v[116:117], v[118:119], v[134:135], v[116:117] op_sel_hi:[0,1,1]
	v_perm_b32 v106, v4, v0, s37
	v_mbcnt_lo_u32_b32 v0, -1, 0
	s_add_i32 s2, s2, 64
	s_bfe_u32 s36, s40, 0x20007
	v_perm_b32 v105, v12, v8, s37
	v_cvt_pk_bf16_f32 v8, v116, s0
	v_cvt_pk_bf16_f32 v12, v117, s0
	v_mbcnt_hi_u32_b32 v0, -1, v0
	s_mul_hi_i32 s3, s2, 0x8800
	s_mul_i32 s2, s2, 0x8800
	s_mulk_i32 s36, 0x2200
	v_perm_b32 v107, v12, v8, s37
	v_and_b32_e32 v8, 64, v0
	s_add_u32 s2, s2, s36
	v_xor_b32_e32 v4, 16, v0
	v_add_u32_e32 v8, 64, v8
	s_addc_u32 s3, s3, 0
	v_cmp_lt_i32_e32 vcc, v4, v8
	s_add_u32 s2, s30, s2
	v_lshlrev_b32_e32 v16, 2, v126
	v_cndmask_b32_e32 v4, v0, v4, vcc
	s_addc_u32 s3, s31, s3
	v_lshlrev_b32_e32 v131, 2, v4
	v_xor_b32_e32 v4, 32, v0
	v_lshl_add_u64 v[116:117], s[2:3], 0, v[16:17]
	s_mov_b64 s[2:3], 0x1700100
	v_cmp_lt_i32_e32 vcc, v4, v8
	v_lshl_add_u64 v[116:117], v[116:117], 0, s[2:3]
	s_mul_i32 s2, s43, 0x440
	v_cndmask_b32_e32 v0, v0, v4, vcc
	v_subrev_u32_e32 v16, s2, v127
	v_lshlrev_b32_e32 v132, 2, v0
	v_xor_b32_e32 v0, 0x80000000, v1
	v_mov_b32_e32 v23, v22
	v_xor_b32_e32 v24, 0x80000000, v25
	v_xor_b32_e32 v4, 0x80000000, v5
	v_mov_b32_e32 v45, v44
	v_xor_b32_e32 v46, 0x80000000, v47
	v_xor_b32_e32 v8, 0x80000000, v9
	v_mov_b32_e32 v67, v66
	v_xor_b32_e32 v68, 0x80000000, v69
	v_xor_b32_e32 v12, 0x80000000, v13
	v_mov_b32_e32 v89, v88
	v_xor_b32_e32 v90, 0x80000000, v91
	v_subrev_u32_e32 v16, 32, v16
	s_mov_b64 s[2:3], 0x200
	v_mov_b32_e32 v137, v17
	v_mov_b32_e32 v135, v17
	v_mov_b32_e32 v133, v17
	v_mov_b32_e32 v139, v17
	v_mov_b32_e32 v138, v17
	v_mov_b32_e32 v136, v17
	v_mov_b32_e32 v134, v17
	v_and_b32_e32 v244, 16, v126
	v_and_b32_e32 v245, 32, v126
	v_cmp_ne_u32_e64 s[96:97], 0, v244
	v_cmp_ne_u32_e32 vcc, 0, v245
	s_nop 1
	v_cndmask_b32_e32 v244, v2, v10, vcc
	v_cndmask_b32_e32 v245, v6, v14, vcc
	v_cndmask_b32_e64 v242, v244, v245, s[96:97]
	v_cndmask_b32_e32 v244, v3, v11, vcc
	v_cndmask_b32_e32 v245, v7, v15, vcc
	v_cndmask_b32_e64 v243, v244, v245, s[96:97]
	v_mov_b64_e32 v[152:153], v[26:27]
	v_mov_b64_e32 v[154:155], v[28:29]
	v_mov_b64_e32 v[156:157], v[30:31]
	v_mov_b64_e32 v[158:159], v[32:33]
	v_mov_b64_e32 v[160:161], v[34:35]
	v_mov_b64_e32 v[162:163], v[36:37]
	v_mov_b64_e32 v[164:165], v[38:39]
	v_mov_b64_e32 v[166:167], v[40:41]
	v_mov_b64_e32 v[26:27], v[164:165]
	v_mov_b64_e32 v[28:29], v[152:153]
	v_mov_b64_e32 v[30:31], v[156:157]
	v_mov_b64_e32 v[32:33], v[160:161]
	v_mov_b64_e32 v[34:35], v[166:167]
	v_mov_b64_e32 v[36:37], v[154:155]
	v_mov_b64_e32 v[38:39], v[158:159]
	v_mov_b64_e32 v[40:41], v[162:163]
	v_mov_b64_e32 v[152:153], v[48:49]
	v_mov_b64_e32 v[154:155], v[50:51]
	v_mov_b64_e32 v[156:157], v[52:53]
	v_mov_b64_e32 v[158:159], v[54:55]
	v_mov_b64_e32 v[160:161], v[56:57]
	v_mov_b64_e32 v[162:163], v[58:59]
	v_mov_b64_e32 v[164:165], v[60:61]
	v_mov_b64_e32 v[166:167], v[62:63]
	v_mov_b64_e32 v[48:49], v[164:165]
	v_mov_b64_e32 v[50:51], v[152:153]
	v_mov_b64_e32 v[52:53], v[156:157]
	v_mov_b64_e32 v[54:55], v[160:161]
	v_mov_b64_e32 v[56:57], v[166:167]
	v_mov_b64_e32 v[58:59], v[154:155]
	v_mov_b64_e32 v[60:61], v[158:159]
	v_mov_b64_e32 v[62:63], v[162:163]
	v_mov_b64_e32 v[152:153], v[70:71]
	v_mov_b64_e32 v[154:155], v[72:73]
	v_mov_b64_e32 v[156:157], v[74:75]
	v_mov_b64_e32 v[158:159], v[76:77]
	v_mov_b64_e32 v[160:161], v[78:79]
	v_mov_b64_e32 v[162:163], v[80:81]
	v_mov_b64_e32 v[164:165], v[82:83]
	v_mov_b64_e32 v[166:167], v[84:85]
	v_mov_b64_e32 v[70:71], v[164:165]
	v_mov_b64_e32 v[72:73], v[152:153]
	v_mov_b64_e32 v[74:75], v[156:157]
	v_mov_b64_e32 v[76:77], v[160:161]
	v_mov_b64_e32 v[78:79], v[166:167]
	v_mov_b64_e32 v[80:81], v[154:155]
	v_mov_b64_e32 v[82:83], v[158:159]
	v_mov_b64_e32 v[84:85], v[162:163]
	v_mov_b64_e32 v[152:153], v[92:93]
	v_mov_b64_e32 v[154:155], v[94:95]
	v_mov_b64_e32 v[156:157], v[96:97]
	v_mov_b64_e32 v[158:159], v[98:99]
	v_mov_b64_e32 v[160:161], v[100:101]
	v_mov_b64_e32 v[162:163], v[102:103]
	v_mov_b64_e32 v[164:165], v[104:105]
	v_mov_b64_e32 v[166:167], v[106:107]
	v_mov_b64_e32 v[92:93], v[164:165]
	v_mov_b64_e32 v[94:95], v[152:153]
	v_mov_b64_e32 v[96:97], v[156:157]
	v_mov_b64_e32 v[98:99], v[160:161]
	v_mov_b64_e32 v[100:101], v[166:167]
	v_mov_b64_e32 v[102:103], v[154:155]
	v_mov_b64_e32 v[104:105], v[158:159]
	v_mov_b64_e32 v[106:107], v[162:163]
	s_nop 1

; template <int DIR>
; __device__ __forceinline__ void s5_local_dir(const bf16_t* UZ, unsigned char* ws, int gw, int NGW, int lane) {
;     ...
; #pragma unroll
;         for (int t = 0; t < 4; ++t) {
;             f32x4 cr = {0.f, 0.f, 0.f, 0.f}, ci = {0.f, 0.f, 0.f, 0.f};
; #pragma unroll
;             for (int m = 0; m < 4; ++m) {
;                 cr = __builtin_amdgcn_mfma_f32_16x16x16bf16_1k(Uf[m], Bre[m][t], cr, 0, 0, 0);
;                 ci = __builtin_amdgcn_mfma_f32_16x16x16bf16_1k(Uf[m], Bim[m][t], ci, 0, 0, 0);
;             }
;             f32x2 s2 = {DIR ? cr[3] : cr[0], DIR ? ci[3] : ci[0]};
; #pragma unroll
;             for (int ii = 1; ii < 4; ++ii) { const int i = DIR ? 3 - ii : ii;
;                 s2 = cmac(s2, (f32x2){a1r[t], a1r[t]}, (f32x2){-a1i[t], a1i[t]}, (f32x2){cr[i], ci[i]}); }
;             s2 = cmac(s2, (f32x2){wr_[t], wr_[t]}, (f32x2){-wi_[t], wi_[t]}, (f32x2){0.f, 0.f});
;             float sr = s2.x, si = s2.y;
;             sr += __shfl_xor(sr, 16); si += __shfl_xor(si, 16); sr += __shfl_xor(sr, 32); si += __shfl_xor(si, 32);
;             if (fq == 0) { e[16 * t + fr] = Rr[t]; e[64 + 16 * t + fr] = Ri[t]; }
;             const float nr = fmaf(a64r[t], Rr[t], fmaf(-a64i[t], Ri[t], sr)), ni = fmaf(a64r[t], Ri[t], fmaf(a64i[t], Rr[t], si)); Rr[t] = nr; Ri[t] = ni;
;         }
;     }
.LBB0_652:
	global_store_dword v[116:117], v240, off offset:-256
	global_store_dword v[116:117], v241, off
	s_waitcnt vmcnt(9)
	v_mfma_f32_16x16x32_bf16 v[140:143], v[108:111], v[26:29], 0
	v_mfma_f32_16x16x32_bf16 v[144:147], v[108:111], v[34:37], 0
	v_mfma_f32_16x16x32_bf16 v[196:199], v[108:111], v[48:51], 0
	v_mfma_f32_16x16x32_bf16 v[200:203], v[108:111], v[56:59], 0
	v_mfma_f32_16x16x32_bf16 v[208:211], v[108:111], v[70:73], 0
	v_mfma_f32_16x16x32_bf16 v[212:215], v[108:111], v[78:81], 0
	v_mfma_f32_16x16x32_bf16 v[228:231], v[108:111], v[92:95], 0
	v_mfma_f32_16x16x32_bf16 v[184:187], v[108:111], v[100:103], 0
	v_mfma_f32_16x16x32_bf16 v[140:143], v[112:115], v[30:33], v[140:143]
	v_mfma_f32_16x16x32_bf16 v[144:147], v[112:115], v[38:41], v[144:147]
	v_mfma_f32_16x16x32_bf16 v[196:199], v[112:115], v[52:55], v[196:199]
	v_mfma_f32_16x16x32_bf16 v[200:203], v[112:115], v[60:63], v[200:203]
	v_mfma_f32_16x16x32_bf16 v[208:211], v[112:115], v[74:77], v[208:211]
	v_mfma_f32_16x16x32_bf16 v[212:215], v[112:115], v[82:85], v[212:215]
	v_mfma_f32_16x16x32_bf16 v[228:231], v[112:115], v[96:99], v[228:231]
	v_mfma_f32_16x16x32_bf16 v[184:187], v[112:115], v[104:107], v[184:187]
	s_nop 6
	v_mov_b32_e32 v148, v143
	v_mov_b32_e32 v204, v199
	v_mov_b32_e32 v216, v211
	v_mov_b32_e32 v190, v231
	v_mov_b32_e32 v149, v147
	v_mov_b32_e32 v205, v203
	v_mov_b32_e32 v217, v215
	v_mov_b32_e32 v191, v187
	v_mov_b32_e32 v150, v142
	v_mov_b32_e32 v206, v198
	v_mov_b32_e32 v218, v210
	v_mov_b32_e32 v188, v230
	v_mov_b32_e32 v151, v146
	v_mov_b32_e32 v207, v202
	v_mov_b32_e32 v219, v214
	v_mov_b32_e32 v189, v186
	v_pk_fma_f32 v[148:149], v[20:21], v[148:149], v[150:151]
	v_pk_fma_f32 v[204:205], v[42:43], v[204:205], v[206:207]
	v_pk_fma_f32 v[216:217], v[64:65], v[216:217], v[218:219]
	v_pk_fma_f32 v[188:189], v[86:87], v[190:191], v[188:189]
	v_mov_b32_e32 v142, v147
	v_mov_b32_e32 v198, v203
	v_mov_b32_e32 v210, v215
	v_mov_b32_e32 v230, v187
	v_pk_fma_f32 v[142:143], v[0:1], v[142:143], v[148:149]
	v_pk_fma_f32 v[198:199], v[4:5], v[198:199], v[204:205]
	v_pk_fma_f32 v[210:211], v[8:9], v[210:211], v[216:217]
	v_pk_fma_f32 v[186:187], v[12:13], v[230:231], v[188:189]
	v_mov_b32_e32 v146, v141
	v_mov_b32_e32 v202, v197
	v_mov_b32_e32 v214, v209
	v_mov_b32_e32 v188, v229
	v_mov_b32_e32 v147, v145
	v_mov_b32_e32 v203, v201
	v_mov_b32_e32 v215, v213
	v_mov_b32_e32 v189, v185
	v_pk_fma_f32 v[146:147], v[20:21], v[142:143], v[146:147]
	v_pk_fma_f32 v[202:203], v[42:43], v[198:199], v[202:203]
	v_pk_fma_f32 v[214:215], v[64:65], v[210:211], v[214:215]
	v_pk_fma_f32 v[188:189], v[86:87], v[186:187], v[188:189]
	v_mov_b32_e32 v141, v144
	v_mov_b32_e32 v197, v200
	v_mov_b32_e32 v209, v212
	v_mov_b32_e32 v229, v184
	v_pk_fma_f32 v[142:143], v[0:1], v[142:143], v[146:147] op_sel:[0,1,0] op_sel_hi:[1,0,1]
	v_pk_fma_f32 v[198:199], v[4:5], v[198:199], v[202:203] op_sel:[0,1,0] op_sel_hi:[1,0,1]
	v_pk_fma_f32 v[210:211], v[8:9], v[210:211], v[214:215] op_sel:[0,1,0] op_sel_hi:[1,0,1]
	v_pk_fma_f32 v[186:187], v[12:13], v[186:187], v[188:189] op_sel:[0,1,0] op_sel_hi:[1,0,1]
	s_nop 0
	s_nop 0
	s_nop 0
	s_nop 0
	v_pk_fma_f32 v[140:141], v[20:21], v[142:143], v[140:141]
	v_pk_fma_f32 v[196:197], v[42:43], v[198:199], v[196:197]
	v_pk_fma_f32 v[208:209], v[64:65], v[210:211], v[208:209]
	v_pk_fma_f32 v[184:185], v[86:87], v[186:187], v[228:229]
	s_nop 0
	s_nop 0
	s_nop 0
	s_nop 0
	v_pk_fma_f32 v[140:141], v[0:1], v[142:143], v[140:141] op_sel:[0,1,0] op_sel_hi:[1,0,1]
	v_pk_fma_f32 v[196:197], v[4:5], v[198:199], v[196:197] op_sel:[0,1,0] op_sel_hi:[1,0,1]
	v_pk_fma_f32 v[208:209], v[8:9], v[210:211], v[208:209] op_sel:[0,1,0] op_sel_hi:[1,0,1]
	v_pk_fma_f32 v[184:185], v[12:13], v[186:187], v[184:185] op_sel:[0,1,0] op_sel_hi:[1,0,1]
	s_nop 0
	s_nop 0
	s_nop 0
	s_nop 0
	v_pk_fma_f32 v[142:143], v[22:23], v[140:141], 0 op_sel_hi:[1,1,0]
	v_pk_fma_f32 v[198:199], v[44:45], v[196:197], 0 op_sel_hi:[1,1,0]
	v_pk_fma_f32 v[210:211], v[66:67], v[208:209], 0 op_sel_hi:[1,1,0]
	v_pk_fma_f32 v[186:187], v[88:89], v[184:185], 0 op_sel_hi:[1,1,0]
	s_nop 0
	s_nop 0
	s_nop 0
	s_nop 0
	v_pk_fma_f32 v[140:141], v[24:25], v[140:141], v[142:143] op_sel:[0,1,0] op_sel_hi:[1,0,1]
	v_pk_fma_f32 v[196:197], v[46:47], v[196:197], v[198:199] op_sel:[0,1,0] op_sel_hi:[1,0,1]
	v_pk_fma_f32 v[208:209], v[68:69], v[208:209], v[210:211] op_sel:[0,1,0] op_sel_hi:[1,0,1]
	v_pk_fma_f32 v[184:185], v[90:91], v[184:185], v[186:187] op_sel:[0,1,0] op_sel_hi:[1,0,1]
	s_nop 1
	v_permlane32_swap_b32_e32 v140, v208
	v_permlane32_swap_b32_e32 v141, v209
	v_permlane32_swap_b32_e32 v196, v184
	v_permlane32_swap_b32_e32 v197, v185
	v_add_f32_e32 v140, v140, v208
	v_add_f32_e32 v196, v196, v184
	v_add_f32_e32 v141, v141, v209
	v_add_f32_e32 v197, v197, v185
	s_nop 0
	v_permlane16_swap_b32_e32 v140, v196
	v_permlane16_swap_b32_e32 v141, v197
	v_add_f32_e32 v140, v140, v196
	v_add_f32_e32 v141, v141, v197
	v_fma_f32 v244, -v243, v241, v140
	v_fma_f32 v245, v243, v240, v141
	v_fma_f32 v240, v242, v240, v244
	v_fma_f32 v241, v242, v241, v245
	v_lshl_add_u64 v[116:117], v[116:117], 0, s[2:3]
	v_subrev_u32_e32 v16, 64, v16
	s_and_b64 vcc, exec, s[36:37]
	s_cbranch_vccnz .LBB0_684
	s_mov_b32 s38, s49
	s_waitcnt vmcnt(3)
	v_mov_b32_e32 v110, v118
	v_mov_b32_e32 v111, v119
	s_waitcnt vmcnt(2)
	v_mov_b32_e32 v112, v120
	v_mov_b32_e32 v113, v121
	s_waitcnt vmcnt(1)
	v_mov_b32_e32 v114, v122
	v_mov_b32_e32 v115, v123
	s_waitcnt vmcnt(0)
	v_mov_b32_e32 v108, v124
	v_mov_b32_e32 v109, v125
	s_branch .LBB0_649

; template <int DIR>
; __device__ __forceinline__ void s5_local_dir(const bf16_t* UZ, unsigned char* ws, int gw, int NGW, int lane) {
;     ...
;     const int pair = gw & 127, g = pair & 63, fr = lane & 15, fq = lane >> 4;
;     const bf16_t* Bb = (const bf16_t*)(ws + WS_BB) + (size_t)pair * 128 * 16;
;     bf16x4 Bre[4][4], Bim[4][4]; float a1r[4], a1i[4], a64r[4], a64i[4], wr_[4], wi_[4];
; #pragma unroll
;     for (int t = 0; t < 4; ++t) {
;         const int p = 16 * t + fr;
;         const bf16x4 b_re = *(const bf16x4*)(Bb + (2 * p) * 16 + 4 * fq), b_im = *(const bf16x4*)(Bb + (2 * p + 1) * 16 + 4 * fq);
;         const f32x4 ap = ((const f32x4*)(ws + WS_APOW))[pair * 64 + p];
;         const float ar = ap.x, ai = ap.y;
;         float r2 = ar, i2 = ai; cmul(r2, i2, ar, ai);
;         float r4 = r2, i4 = i2; cmul(r4, i4, r2, i2);
;         float r8 = r4, i8 = i4; cmul(r8, i8, r4, i4);
;         float r12 = r8, i12 = i8; cmul(r12, i12, r4, i4);
;         float r16 = r8, i16 = i8; cmul(r16, i16, r8, i8);
;         float r32 = r16, i32 = i16; cmul(r32, i32, r16, i16);
;         float r48 = r32, i48 = i32; cmul(r48, i48, r16, i16);
;         a1r[t] = ar; a1i[t] = ai; a64r[t] = ap.z; a64i[t] = ap.w;
;         const int e = DIR ? fq : 3 - fq;
;         wr_[t] = e == 0 ? 1.f : e == 1 ? r4 : e == 2 ? r8 : r12; wi_[t] = e == 0 ? 0.f : e == 1 ? i4 : e == 2 ? i8 : i12;
; #pragma unroll
;         for (int m = 0; m < 4; ++m) {
;             const int em = DIR ? m : 3 - m;
;             const float pr = em == 0 ? 1.f : em == 1 ? r16 : em == 2 ? r32 : r48, pi = em == 0 ? 0.f : em == 1 ? i16 : em == 2 ? i32 : i48;
;             Bre[m][t] = cscale_bf(b_re, b_im, pr, pi, false); Bim[m][t] = cscale_bf(b_re, b_im, pr, pi, true);
;         }
;     }
;     const int qd = gw >> 7, b = qd >> 2, q = qd & 3;
;     if (qd >= 16) return;
;     const int c0 = 17 * q, c1 = q < 3 ? c0 + 17 : 67;
;     float Rr[4] = {0.f, 0.f, 0.f, 0.f}, Ri[4] = {0.f, 0.f, 0.f, 0.f};
;     float* ebase = E + ((size_t)((b * 2 + DIR) * 64 + g) * NCHUNK) * 128;
;     bf16x4 Un[4];
;     load_uf(Un, UZ, chunk_rowbase(b, DIR, c0), g, lane);
.LBB0_669:
	s_mul_i32 s24, s37, 17
	s_add_i32 s4, s24, 17
	s_cmp_lg_u32 s37, 3
	s_cselect_b64 s[8:9], -1, 0
	s_and_b64 s[2:3], s[8:9], exec
	s_cselect_b32 s39, s4, 0x43
	s_lshl_b32 s38, s23, 7
	v_mov_b32_e32 v115, 0
	v_mov_b32_e32 v240, 0
	v_mov_b32_e32 v241, 0
	s_cmp_ge_u32 s24, s39
	v_mov_b32_e32 v114, 0
	v_mov_b32_e32 v112, 0
	v_mov_b32_e32 v110, 0
	v_mov_b32_e32 v113, 0
	v_mov_b32_e32 v111, 0
	v_mov_b32_e32 v109, 0
	v_mov_b32_e32 v108, 0
	s_cbranch_scc1 .LBB0_702
	s_lshl_b32 s100, s36, 5
	s_add_u32 s100, s18, s100
	s_addc_u32 s101, s19, 0
	v_add_u32_e32 v160, s25, v127
	v_ashrrev_i32_e32 v161, 31, v160
	v_lshlrev_b64 v[162:163], 12, v[160:161]
	v_lshrrev_b32_e32 v164, 1, v192
	v_and_b32_e32 v164, 24, v164
	v_mov_b32_e32 v165, 0
	v_lshl_add_u64 v[162:163], s[100:101], 0, v[162:163]
	v_lshl_add_u64 v[162:163], v[162:163], 0, v[164:165]
	s_mov_b32 s98, 0x10000
	s_mov_b32 s99, 0
	v_lshl_add_u64 v[164:165], v[162:163], 0, s[98:99]
	v_lshl_add_u64 v[166:167], v[164:165], 0, s[98:99]
	v_lshl_add_u64 v[168:169], v[166:167], 0, s[98:99]
	global_load_dwordx2 v[152:153], v[162:163], off
	global_load_dwordx2 v[154:155], v[164:165], off
	global_load_dwordx2 v[156:157], v[166:167], off
	global_load_dwordx2 v[158:159], v[168:169], off
	s_waitcnt vmcnt(13)
	v_pk_mul_f32 v[22:23], v[0:1], v[0:1] op_sel:[1,1] op_sel_hi:[1,0]
	s_lshl_b32 s2, s36, 5
	v_pk_fma_f32 v[24:25], v[0:1], v[0:1], v[22:23] op_sel_hi:[1,0,1] neg_lo:[0,0,1] neg_hi:[0,0,1]
	v_pk_fma_f32 v[22:23], v[0:1], v[0:1], v[22:23] op_sel_hi:[1,0,1]
	v_mov_b32_e32 v30, v24
	v_pk_mov_b32 v[32:33], v[22:23], v[24:25] op_sel:[1,0]
	v_mov_b32_e32 v31, v23
	v_pk_mul_f32 v[22:23], v[22:23], v[32:33] op_sel:[1,0]
	v_mov_b32_e32 v18, v0
	v_pk_fma_f32 v[32:33], v[24:25], v[30:31], v[22:23] op_sel_hi:[0,1,1] neg_lo:[0,0,1] neg_hi:[0,0,1]
	v_pk_fma_f32 v[22:23], v[24:25], v[30:31], v[22:23] op_sel_hi:[0,1,1]
	v_pk_mov_b32 v[30:31], v[22:23], v[32:33] op_sel:[1,0]
	v_mov_b32_e32 v24, v32
	v_mov_b32_e32 v25, v23
	v_pk_mul_f32 v[30:31], v[22:23], v[30:31] op_sel:[1,0]
	v_mov_b32_e32 v19, v0
	v_pk_fma_f32 v[34:35], v[32:33], v[24:25], v[30:31] op_sel_hi:[0,1,1] neg_lo:[0,0,1] neg_hi:[0,0,1]
	v_pk_fma_f32 v[30:31], v[32:33], v[24:25], v[30:31] op_sel_hi:[0,1,1]
	v_mov_b32_e32 v35, v31
	v_pk_mul_f32 v[36:37], v[34:35], v[34:35]
	v_pk_mul_f32 v[38:39], v[30:31], v[34:35] op_sel:[1,0] op_sel_hi:[0,1]
	v_mov_b32_e32 v40, v36
	v_mov_b32_e32 v41, v38
	v_pk_mov_b32 v[36:37], v[36:37], v[38:39] op_sel:[1,0]
	s_add_u32 s2, s18, s2
	v_pk_add_f32 v[38:39], v[40:41], v[36:37] neg_lo:[0,1] neg_hi:[0,1]
	v_pk_add_f32 v[36:37], v[40:41], v[36:37]
	v_mov_b32_e32 v40, v38
	v_mov_b32_e32 v41, v37
	v_pk_mul_f32 v[44:45], v[40:41], v[40:41]
	v_pk_mul_f32 v[46:47], v[36:37], v[40:41] op_sel:[1,0] op_sel_hi:[0,1]
	v_mov_b32_e32 v52, v44
	v_mov_b32_e32 v53, v46
	v_pk_mov_b32 v[44:45], v[44:45], v[46:47] op_sel:[1,0]
	v_lshrrev_b32_e32 v16, 1, v192
	v_pk_add_f32 v[46:47], v[52:53], v[44:45] neg_lo:[0,1] neg_hi:[0,1]
	v_pk_add_f32 v[44:45], v[52:53], v[44:45]
	v_mov_b32_e32 v52, v46
	v_mov_b32_e32 v53, v45
	v_mul_f32_e32 v0, v37, v45
	v_pk_mov_b32 v[42:43], v[36:37], v[38:39] op_sel:[1,0]
	v_pk_fma_f32 v[40:41], v[40:41], v[52:53], v[0:1] op_sel_hi:[1,1,0] neg_lo:[0,0,1] neg_hi:[0,0,1]
	v_mul_f32_e32 v0, v38, v45
	s_addc_u32 s3, s19, 0
	v_and_b32_e32 v20, 24, v16
	v_mov_b32_e32 v21, 0
	v_pk_fma_f32 v[42:43], v[42:43], v[52:53], v[0:1] op_sel_hi:[1,1,0]
	v_mul_f32_e32 v0, v23, v34
	v_pk_mul_f32 v[24:25], v[24:25], v[34:35]
	v_and_b32_e32 v59, 0xffff0000, v27
	v_lshlrev_b32_e32 v58, 16, v27
	v_lshl_add_u64 v[16:17], s[2:3], 0, v[20:21]
	v_fmac_f32_e32 v0, v32, v31
	v_sub_f32_e32 v20, v24, v25
	v_cmp_eq_u32_e32 vcc, 1, v128
	v_and_b32_e32 v53, 0xffff0000, v28
	v_lshlrev_b32_e32 v52, 16, v28
	v_and_b32_e32 v55, 0xffff0000, v26
	v_lshlrev_b32_e32 v54, 16, v26
	v_and_b32_e32 v57, 0xffff0000, v29
	v_lshlrev_b32_e32 v56, 16, v29
	v_pk_mul_f32 v[28:29], v[42:43], v[58:59] op_sel_hi:[0,1]
	v_cndmask_b32_e32 v20, v20, v34, vcc
	v_cmp_eq_u32_e64 s[2:3], 2, v128
	v_cndmask_b32_e32 v0, v0, v31, vcc
	v_pk_mul_f32 v[26:27], v[42:43], v[54:55] op_sel_hi:[0,1]
	v_pk_fma_f32 v[28:29], v[40:41], v[56:57], v[28:29] op_sel_hi:[0,1,1] neg_lo:[0,0,1] neg_hi:[0,0,1]
	v_pk_mul_f32 v[30:31], v[42:43], v[56:57] op_sel_hi:[0,1]
	v_cndmask_b32_e64 v20, v20, v32, s[2:3]
	v_cndmask_b32_e64 v0, v0, v23, s[2:3]
	v_cmp_eq_u32_e64 s[4:5], 3, v128
	v_pk_fma_f32 v[26:27], v[40:41], v[52:53], v[26:27] op_sel_hi:[0,1,1] neg_lo:[0,0,1] neg_hi:[0,0,1]
	v_cvt_pk_bf16_f32 v23, v28, s0
	v_cvt_pk_bf16_f32 v24, v29, s0
	s_mov_b32 s41, 0x5040100
	v_pk_mul_f32 v[28:29], v[42:43], v[52:53] op_sel_hi:[0,1]
	v_pk_fma_f32 v[30:31], v[40:41], v[58:59], v[30:31] op_sel_hi:[0,1,1]
	v_pk_mul_f32 v[32:33], v[44:45], v[58:59] op_sel:[1,0]
	v_cndmask_b32_e64 v22, v20, 1.0, s[4:5]
	v_cndmask_b32_e64 v25, v0, 0, s[4:5]
	v_cvt_pk_bf16_f32 v0, v26, s0
	v_cvt_pk_bf16_f32 v20, v27, s0
	v_perm_b32 v27, v24, v23, s41
	v_pk_fma_f32 v[28:29], v[40:41], v[54:55], v[28:29] op_sel_hi:[0,1,1]
	v_cvt_pk_bf16_f32 v23, v30, s0
	v_cvt_pk_bf16_f32 v24, v31, s0
	v_pk_mul_f32 v[30:31], v[44:45], v[54:55] op_sel:[1,0]
	v_pk_fma_f32 v[32:33], v[46:47], v[56:57], v[32:33] op_sel_hi:[0,1,1] neg_lo:[0,0,1] neg_hi:[0,0,1]
	v_pk_mul_f32 v[34:35], v[44:45], v[56:57] op_sel:[1,0]
	v_perm_b32 v26, v20, v0, s41
	v_cvt_pk_bf16_f32 v0, v28, s0
	v_cvt_pk_bf16_f32 v20, v29, s0
	v_perm_b32 v29, v24, v23, s41
	v_pk_fma_f32 v[30:31], v[46:47], v[52:53], v[30:31] op_sel_hi:[0,1,1] neg_lo:[0,0,1] neg_hi:[0,0,1]
	v_cvt_pk_bf16_f32 v23, v32, s0
	v_cvt_pk_bf16_f32 v24, v33, s0
	v_pk_mul_f32 v[32:33], v[44:45], v[52:53] op_sel:[1,0]
	v_pk_fma_f32 v[34:35], v[46:47], v[58:59], v[34:35] op_sel_hi:[0,1,1]
	v_pk_mul_f32 v[40:41], v[36:37], v[58:59] op_sel:[1,0]
	v_perm_b32 v28, v20, v0, s41
	v_cvt_pk_bf16_f32 v0, v30, s0
	v_cvt_pk_bf16_f32 v20, v31, s0
	v_perm_b32 v31, v24, v23, s41
	v_pk_fma_f32 v[32:33], v[46:47], v[54:55], v[32:33] op_sel_hi:[0,1,1]
	v_cvt_pk_bf16_f32 v23, v34, s0
	v_cvt_pk_bf16_f32 v24, v35, s0
	v_pk_fma_f32 v[40:41], v[38:39], v[56:57], v[40:41] op_sel_hi:[0,1,1] neg_lo:[0,0,1] neg_hi:[0,0,1]
	s_waitcnt vmcnt(10)
; __device__ __forceinline__ unsigned pk2(float lo, float hi) { f32x2 v = {lo, hi}; nbf2 r = __builtin_convertvector(v, nbf2); return __builtin_bit_cast(unsigned, r); }
; __device__ __forceinline__ bf16x4 cscale_bf(const bf16x4 re, const bf16x4 im, float wr, float wi, bool want_im) {
;     bf16x4 o;
; #pragma unroll
;     for (int k = 0; k < 4; k += 2) {
;         const float r0 = __uint_as_float((unsigned)(unsigned short)re[k] << 16), r1 = __uint_as_float((unsigned)(unsigned short)re[k + 1] << 16);
;         const float i0 = __uint_as_float((unsigned)(unsigned short)im[k] << 16), i1 = __uint_as_float((unsigned)(unsigned short)im[k + 1] << 16);
;         const unsigned w = want_im ? pk2(wr * i0 + wi * r0, wr * i1 + wi * r1) : pk2(wr * r0 - wi * i0, wr * r1 - wi * i1);
;         o[k] = (short)(w & 0xffffu); o[k + 1] = (short)(w >> 16);
;     }
;     return o;
; }
; template <int DIR>
; __device__ __forceinline__ void s5_local_dir(const bf16_t* UZ, unsigned char* ws, int gw, int NGW, int lane) {
;     ...
;     for (int t = 0; t < 4; ++t) {
;         const int p = 16 * t + fr;
;         const bf16x4 b_re = *(const bf16x4*)(Bb + (2 * p) * 16 + 4 * fq), b_im = *(const bf16x4*)(Bb + (2 * p + 1) * 16 + 4 * fq);
;         const f32x4 ap = ((const f32x4*)(ws + WS_APOW))[pair * 64 + p];
;         const float ar = ap.x, ai = ap.y;
;         float r2 = ar, i2 = ai; cmul(r2, i2, ar, ai);
;         float r4 = r2, i4 = i2; cmul(r4, i4, r2, i2);
;         float r8 = r4, i8 = i4; cmul(r8, i8, r4, i4);
;         float r12 = r8, i12 = i8; cmul(r12, i12, r4, i4);
;         float r16 = r8, i16 = i8; cmul(r16, i16, r8, i8);
;         float r32 = r16, i32 = i16; cmul(r32, i32, r16, i16);
;         float r48 = r32, i48 = i32; cmul(r48, i48, r16, i16);
;         a1r[t] = ar; a1i[t] = ai; a64r[t] = ap.z; a64i[t] = ap.w;
;         const int e = DIR ? fq : 3 - fq;
;         wr_[t] = e == 0 ? 1.f : e == 1 ? r4 : e == 2 ? r8 : r12; wi_[t] = e == 0 ? 0.f : e == 1 ? i4 : e == 2 ? i8 : i12;
; #pragma unroll
;         for (int m = 0; m < 4; ++m) {
;             const int em = DIR ? m : 3 - m;
;             const float pr = em == 0 ? 1.f : em == 1 ? r16 : em == 2 ? r32 : r48, pi = em == 0 ? 0.f : em == 1 ? i16 : em == 2 ? i32 : i48;
;             Bre[m][t] = cscale_bf(b_re, b_im, pr, pi, false); Bim[m][t] = cscale_bf(b_re, b_im, pr, pi, true);
;         }
	v_pk_mul_f32 v[44:45], v[4:5], v[4:5] op_sel:[1,1] op_sel_hi:[1,0]
	v_perm_b32 v30, v20, v0, s41
	v_cvt_pk_bf16_f32 v20, v33, s0
	v_perm_b32 v33, v24, v23, s41
	v_pk_mul_f32 v[34:35], v[36:37], v[54:55] op_sel:[1,0]
	v_cvt_pk_bf16_f32 v23, v40, s0
	v_cvt_pk_bf16_f32 v24, v41, s0
	v_pk_mul_f32 v[40:41], v[36:37], v[52:53] op_sel:[1,0]
	v_pk_mul_f32 v[36:37], v[36:37], v[56:57] op_sel:[1,0]
	v_pk_fma_f32 v[46:47], v[4:5], v[4:5], v[44:45] op_sel_hi:[1,0,1] neg_lo:[0,0,1] neg_hi:[0,0,1]
	v_pk_fma_f32 v[44:45], v[4:5], v[4:5], v[44:45] op_sel_hi:[1,0,1]
	v_pk_fma_f32 v[34:35], v[38:39], v[52:53], v[34:35] op_sel_hi:[0,1,1] neg_lo:[0,0,1] neg_hi:[0,0,1]
	v_pk_fma_f32 v[36:37], v[38:39], v[58:59], v[36:37] op_sel_hi:[0,1,1]
	v_pk_fma_f32 v[38:39], v[38:39], v[54:55], v[40:41] op_sel_hi:[0,1,1]
	v_xor_b32_e32 v41, 0x80000000, v55
	v_xor_b32_e32 v40, 0x80000000, v54
	v_pk_fma_f32 v[42:43], v[52:53], 0, v[54:55] op_sel_hi:[1,0,1]
	v_pk_mov_b32 v[54:55], v[44:45], v[46:47] op_sel:[1,0]
	v_pk_fma_f32 v[40:41], v[40:41], 0, v[52:53] op_sel_hi:[1,0,1]
	v_mov_b32_e32 v52, v46
	v_mov_b32_e32 v53, v45
	v_pk_mul_f32 v[44:45], v[44:45], v[54:55] op_sel:[1,0]
	v_cvt_pk_bf16_f32 v0, v32, s0
	v_pk_fma_f32 v[54:55], v[46:47], v[52:53], v[44:45] op_sel_hi:[0,1,1] neg_lo:[0,0,1] neg_hi:[0,0,1]
	v_pk_fma_f32 v[44:45], v[46:47], v[52:53], v[44:45] op_sel_hi:[0,1,1]
	v_perm_b32 v32, v20, v0, s41
	v_cvt_pk_bf16_f32 v0, v34, s0
	v_cvt_pk_bf16_f32 v20, v35, s0
	v_pk_mov_b32 v[52:53], v[44:45], v[54:55] op_sel:[1,0]
	v_perm_b32 v34, v20, v0, s41
	v_cvt_pk_bf16_f32 v0, v38, s0
	v_cvt_pk_bf16_f32 v20, v39, s0
	v_xor_b32_e32 v39, 0x80000000, v59
	v_xor_b32_e32 v38, 0x80000000, v58
	v_mov_b32_e32 v46, v54
	v_mov_b32_e32 v47, v45
	v_pk_mul_f32 v[52:53], v[44:45], v[52:53] op_sel:[1,0]
	v_perm_b32 v35, v24, v23, s41
	v_cvt_pk_bf16_f32 v23, v36, s0
	v_perm_b32 v36, v20, v0, s41
	v_pk_fma_f32 v[38:39], v[38:39], 0, v[56:57] op_sel_hi:[1,0,1]
	v_cvt_pk_bf16_f32 v0, v40, s0
	v_cvt_pk_bf16_f32 v20, v41, s0
	v_pk_fma_f32 v[40:41], v[56:57], 0, v[58:59] op_sel_hi:[1,0,1]
	v_pk_fma_f32 v[56:57], v[54:55], v[46:47], v[52:53] op_sel_hi:[0,1,1] neg_lo:[0,0,1] neg_hi:[0,0,1]
	v_pk_fma_f32 v[52:53], v[54:55], v[46:47], v[52:53] op_sel_hi:[0,1,1]
	v_mov_b32_e32 v57, v53
	v_pk_mul_f32 v[58:59], v[56:57], v[56:57]
	v_pk_mul_f32 v[60:61], v[52:53], v[56:57] op_sel:[1,0] op_sel_hi:[0,1]
	v_mov_b32_e32 v62, v58
	v_mov_b32_e32 v63, v60
	v_pk_mov_b32 v[58:59], v[58:59], v[60:61] op_sel:[1,0]
	v_cvt_pk_bf16_f32 v24, v37, s0
	v_pk_add_f32 v[60:61], v[62:63], v[58:59] neg_lo:[0,1] neg_hi:[0,1]
	v_pk_add_f32 v[58:59], v[62:63], v[58:59]
	v_mov_b32_e32 v62, v60
	v_mov_b32_e32 v63, v59
	v_pk_mul_f32 v[66:67], v[62:63], v[62:63]
	v_pk_mul_f32 v[68:69], v[58:59], v[62:63] op_sel:[1,0] op_sel_hi:[0,1]
	v_mov_b32_e32 v74, v66
	v_mov_b32_e32 v75, v68
	v_pk_mov_b32 v[66:67], v[66:67], v[68:69] op_sel:[1,0]
	v_perm_b32 v37, v24, v23, s41
	v_cvt_pk_bf16_f32 v23, v38, s0
	v_cvt_pk_bf16_f32 v24, v39, s0
	v_perm_b32 v38, v20, v0, s41
	v_cvt_pk_bf16_f32 v0, v42, s0
	v_cvt_pk_bf16_f32 v20, v43, s0
	v_pk_add_f32 v[68:69], v[74:75], v[66:67] neg_lo:[0,1] neg_hi:[0,1]
	v_pk_add_f32 v[66:67], v[74:75], v[66:67]
	v_perm_b32 v39, v24, v23, s41
	v_cvt_pk_bf16_f32 v23, v40, s0
	v_perm_b32 v40, v20, v0, s41
	v_mov_b32_e32 v74, v68
	v_mov_b32_e32 v75, v67
	v_mul_f32_e32 v0, v59, v67
	v_pk_mov_b32 v[64:65], v[58:59], v[60:61] op_sel:[1,0]
	v_pk_fma_f32 v[62:63], v[62:63], v[74:75], v[0:1] op_sel_hi:[1,1,0] neg_lo:[0,0,1] neg_hi:[0,0,1]
	v_mul_f32_e32 v0, v60, v67
	v_pk_fma_f32 v[64:65], v[64:65], v[74:75], v[0:1] op_sel_hi:[1,1,0]
	v_mul_f32_e32 v0, v45, v56
	v_pk_mul_f32 v[46:47], v[46:47], v[56:57]
	v_and_b32_e32 v81, 0xffff0000, v51
	v_lshlrev_b32_e32 v80, 16, v51
	v_mov_b32_e32 v42, v4
	v_mov_b32_e32 v43, v4
	v_fmac_f32_e32 v0, v54, v53
	v_sub_f32_e32 v4, v46, v47
	v_and_b32_e32 v77, 0xffff0000, v50
	v_lshlrev_b32_e32 v76, 16, v50
	v_and_b32_e32 v79, 0xffff0000, v49
	v_lshlrev_b32_e32 v78, 16, v49
	v_pk_mul_f32 v[50:51], v[64:65], v[80:81] op_sel_hi:[0,1]
	v_cvt_pk_bf16_f32 v24, v41, s0
	v_cndmask_b32_e32 v4, v4, v56, vcc
	v_cndmask_b32_e32 v0, v0, v53, vcc
	v_and_b32_e32 v75, 0xffff0000, v48
	v_lshlrev_b32_e32 v74, 16, v48
	v_pk_mul_f32 v[48:49], v[64:65], v[76:77] op_sel_hi:[0,1]
	v_pk_fma_f32 v[50:51], v[62:63], v[78:79], v[50:51] op_sel_hi:[0,1,1] neg_lo:[0,0,1] neg_hi:[0,0,1]
	v_pk_mul_f32 v[52:53], v[64:65], v[78:79] op_sel_hi:[0,1]
	v_perm_b32 v41, v24, v23, s41
	v_cndmask_b32_e64 v4, v4, v54, s[2:3]
	v_cndmask_b32_e64 v0, v0, v45, s[2:3]
	v_pk_fma_f32 v[48:49], v[62:63], v[74:75], v[48:49] op_sel_hi:[0,1,1] neg_lo:[0,0,1] neg_hi:[0,0,1]
	v_cvt_pk_bf16_f32 v20, v50, s0
	v_cvt_pk_bf16_f32 v23, v51, s0
	v_pk_mul_f32 v[50:51], v[64:65], v[74:75] op_sel_hi:[0,1]
	v_pk_fma_f32 v[52:53], v[62:63], v[80:81], v[52:53] op_sel_hi:[0,1,1]
	v_pk_mul_f32 v[54:55], v[66:67], v[80:81] op_sel:[1,0]
	v_cndmask_b32_e64 v44, v4, 1.0, s[4:5]
	v_cndmask_b32_e64 v47, v0, 0, s[4:5]
	v_cvt_pk_bf16_f32 v0, v48, s0
	v_cvt_pk_bf16_f32 v4, v49, s0
	v_perm_b32 v49, v23, v20, s41
	v_pk_fma_f32 v[50:51], v[62:63], v[76:77], v[50:51] op_sel_hi:[0,1,1]
	v_cvt_pk_bf16_f32 v20, v52, s0
	v_cvt_pk_bf16_f32 v23, v53, s0
	v_pk_mul_f32 v[52:53], v[66:67], v[76:77] op_sel:[1,0]
	v_pk_fma_f32 v[54:55], v[68:69], v[78:79], v[54:55] op_sel_hi:[0,1,1] neg_lo:[0,0,1] neg_hi:[0,0,1]
	v_pk_mul_f32 v[56:57], v[66:67], v[78:79] op_sel:[1,0]
	v_perm_b32 v48, v4, v0, s41
	v_cvt_pk_bf16_f32 v0, v50, s0
	v_cvt_pk_bf16_f32 v4, v51, s0
	v_perm_b32 v51, v23, v20, s41
	v_pk_fma_f32 v[52:53], v[68:69], v[74:75], v[52:53] op_sel_hi:[0,1,1] neg_lo:[0,0,1] neg_hi:[0,0,1]
	v_cvt_pk_bf16_f32 v20, v54, s0
	v_cvt_pk_bf16_f32 v23, v55, s0
	v_pk_mul_f32 v[54:55], v[66:67], v[74:75] op_sel:[1,0]
	v_pk_fma_f32 v[56:57], v[68:69], v[80:81], v[56:57] op_sel_hi:[0,1,1]
	v_pk_mul_f32 v[62:63], v[58:59], v[80:81] op_sel:[1,0]
	v_perm_b32 v50, v4, v0, s41
	v_cvt_pk_bf16_f32 v0, v52, s0
	v_cvt_pk_bf16_f32 v4, v53, s0
	v_perm_b32 v53, v23, v20, s41
	v_pk_fma_f32 v[54:55], v[68:69], v[76:77], v[54:55] op_sel_hi:[0,1,1]
	v_cvt_pk_bf16_f32 v20, v56, s0
	v_cvt_pk_bf16_f32 v23, v57, s0
	v_pk_fma_f32 v[62:63], v[60:61], v[78:79], v[62:63] op_sel_hi:[0,1,1] neg_lo:[0,0,1] neg_hi:[0,0,1]
	s_waitcnt vmcnt(7)
; __device__ __forceinline__ unsigned pk2(float lo, float hi) { f32x2 v = {lo, hi}; nbf2 r = __builtin_convertvector(v, nbf2); return __builtin_bit_cast(unsigned, r); }
; __device__ __forceinline__ bf16x4 cscale_bf(const bf16x4 re, const bf16x4 im, float wr, float wi, bool want_im) {
;     bf16x4 o;
; #pragma unroll
;     for (int k = 0; k < 4; k += 2) {
;         const float r0 = __uint_as_float((unsigned)(unsigned short)re[k] << 16), r1 = __uint_as_float((unsigned)(unsigned short)re[k + 1] << 16);
;         const float i0 = __uint_as_float((unsigned)(unsigned short)im[k] << 16), i1 = __uint_as_float((unsigned)(unsigned short)im[k + 1] << 16);
;         const unsigned w = want_im ? pk2(wr * i0 + wi * r0, wr * i1 + wi * r1) : pk2(wr * r0 - wi * i0, wr * r1 - wi * i1);
;         o[k] = (short)(w & 0xffffu); o[k + 1] = (short)(w >> 16);
;     }
;     return o;
; }
; template <int DIR>
; __device__ __forceinline__ void s5_local_dir(const bf16_t* UZ, unsigned char* ws, int gw, int NGW, int lane) {
;     ...
;     for (int t = 0; t < 4; ++t) {
;         const int p = 16 * t + fr;
;         const bf16x4 b_re = *(const bf16x4*)(Bb + (2 * p) * 16 + 4 * fq), b_im = *(const bf16x4*)(Bb + (2 * p + 1) * 16 + 4 * fq);
;         const f32x4 ap = ((const f32x4*)(ws + WS_APOW))[pair * 64 + p];
;         const float ar = ap.x, ai = ap.y;
;         float r2 = ar, i2 = ai; cmul(r2, i2, ar, ai);
;         float r4 = r2, i4 = i2; cmul(r4, i4, r2, i2);
;         float r8 = r4, i8 = i4; cmul(r8, i8, r4, i4);
;         float r12 = r8, i12 = i8; cmul(r12, i12, r4, i4);
;         float r16 = r8, i16 = i8; cmul(r16, i16, r8, i8);
;         float r32 = r16, i32 = i16; cmul(r32, i32, r16, i16);
;         float r48 = r32, i48 = i32; cmul(r48, i48, r16, i16);
;         a1r[t] = ar; a1i[t] = ai; a64r[t] = ap.z; a64i[t] = ap.w;
;         const int e = DIR ? fq : 3 - fq;
;         wr_[t] = e == 0 ? 1.f : e == 1 ? r4 : e == 2 ? r8 : r12; wi_[t] = e == 0 ? 0.f : e == 1 ? i4 : e == 2 ? i8 : i12;
; #pragma unroll
;         for (int m = 0; m < 4; ++m) {
;             const int em = DIR ? m : 3 - m;
;             const float pr = em == 0 ? 1.f : em == 1 ? r16 : em == 2 ? r32 : r48, pi = em == 0 ? 0.f : em == 1 ? i16 : em == 2 ? i32 : i48;
;             Bre[m][t] = cscale_bf(b_re, b_im, pr, pi, false); Bim[m][t] = cscale_bf(b_re, b_im, pr, pi, true);
;         }
	v_pk_mul_f32 v[66:67], v[8:9], v[8:9] op_sel:[1,1] op_sel_hi:[1,0]
	v_perm_b32 v52, v4, v0, s41
	v_cvt_pk_bf16_f32 v4, v55, s0
	v_perm_b32 v55, v23, v20, s41
	v_pk_mul_f32 v[56:57], v[58:59], v[76:77] op_sel:[1,0]
	v_cvt_pk_bf16_f32 v20, v62, s0
	v_cvt_pk_bf16_f32 v23, v63, s0
	v_pk_mul_f32 v[62:63], v[58:59], v[74:75] op_sel:[1,0]
	v_pk_mul_f32 v[58:59], v[58:59], v[78:79] op_sel:[1,0]
	v_pk_fma_f32 v[68:69], v[8:9], v[8:9], v[66:67] op_sel_hi:[1,0,1] neg_lo:[0,0,1] neg_hi:[0,0,1]
	v_pk_fma_f32 v[66:67], v[8:9], v[8:9], v[66:67] op_sel_hi:[1,0,1]
	v_pk_fma_f32 v[56:57], v[60:61], v[74:75], v[56:57] op_sel_hi:[0,1,1] neg_lo:[0,0,1] neg_hi:[0,0,1]
	v_pk_fma_f32 v[58:59], v[60:61], v[80:81], v[58:59] op_sel_hi:[0,1,1]
	v_pk_fma_f32 v[60:61], v[60:61], v[76:77], v[62:63] op_sel_hi:[0,1,1]
	v_xor_b32_e32 v63, 0x80000000, v77
	v_xor_b32_e32 v62, 0x80000000, v76
	v_pk_fma_f32 v[64:65], v[74:75], 0, v[76:77] op_sel_hi:[1,0,1]
	v_pk_mov_b32 v[76:77], v[66:67], v[68:69] op_sel:[1,0]
	v_pk_fma_f32 v[62:63], v[62:63], 0, v[74:75] op_sel_hi:[1,0,1]
	v_mov_b32_e32 v74, v68
	v_mov_b32_e32 v75, v67
	v_pk_mul_f32 v[66:67], v[66:67], v[76:77] op_sel:[1,0]
	v_cvt_pk_bf16_f32 v0, v54, s0
	v_pk_fma_f32 v[76:77], v[68:69], v[74:75], v[66:67] op_sel_hi:[0,1,1] neg_lo:[0,0,1] neg_hi:[0,0,1]
	v_pk_fma_f32 v[66:67], v[68:69], v[74:75], v[66:67] op_sel_hi:[0,1,1]
	v_perm_b32 v54, v4, v0, s41
	v_cvt_pk_bf16_f32 v0, v56, s0
	v_cvt_pk_bf16_f32 v4, v57, s0
	v_pk_mov_b32 v[74:75], v[66:67], v[76:77] op_sel:[1,0]
	v_perm_b32 v56, v4, v0, s41
	v_cvt_pk_bf16_f32 v0, v60, s0
	v_cvt_pk_bf16_f32 v4, v61, s0
	v_xor_b32_e32 v61, 0x80000000, v81
	v_xor_b32_e32 v60, 0x80000000, v80
	v_mov_b32_e32 v68, v76
	v_mov_b32_e32 v69, v67
	v_pk_mul_f32 v[74:75], v[66:67], v[74:75] op_sel:[1,0]
	v_perm_b32 v57, v23, v20, s41
	v_cvt_pk_bf16_f32 v20, v58, s0
	v_perm_b32 v58, v4, v0, s41
	v_pk_fma_f32 v[60:61], v[60:61], 0, v[78:79] op_sel_hi:[1,0,1]
	v_cvt_pk_bf16_f32 v0, v62, s0
	v_cvt_pk_bf16_f32 v4, v63, s0
	v_pk_fma_f32 v[62:63], v[78:79], 0, v[80:81] op_sel_hi:[1,0,1]
	v_pk_fma_f32 v[78:79], v[76:77], v[68:69], v[74:75] op_sel_hi:[0,1,1] neg_lo:[0,0,1] neg_hi:[0,0,1]
	v_pk_fma_f32 v[74:75], v[76:77], v[68:69], v[74:75] op_sel_hi:[0,1,1]
	v_mov_b32_e32 v79, v75
	v_pk_mul_f32 v[80:81], v[78:79], v[78:79]
	v_pk_mul_f32 v[82:83], v[74:75], v[78:79] op_sel:[1,0] op_sel_hi:[0,1]
	v_mov_b32_e32 v84, v80
	v_mov_b32_e32 v85, v82
	v_pk_mov_b32 v[80:81], v[80:81], v[82:83] op_sel:[1,0]
	v_cvt_pk_bf16_f32 v23, v59, s0
	v_pk_add_f32 v[82:83], v[84:85], v[80:81] neg_lo:[0,1] neg_hi:[0,1]
	v_pk_add_f32 v[80:81], v[84:85], v[80:81]
	v_mov_b32_e32 v84, v82
	v_mov_b32_e32 v85, v81
	v_pk_mul_f32 v[92:93], v[84:85], v[84:85]
	v_pk_mul_f32 v[94:95], v[80:81], v[84:85] op_sel:[1,0] op_sel_hi:[0,1]
	v_mov_b32_e32 v96, v92
	v_mov_b32_e32 v97, v94
	v_pk_mov_b32 v[92:93], v[92:93], v[94:95] op_sel:[1,0]
	v_perm_b32 v59, v23, v20, s41
	v_cvt_pk_bf16_f32 v20, v60, s0
	v_cvt_pk_bf16_f32 v23, v61, s0
	v_perm_b32 v60, v4, v0, s41
	v_cvt_pk_bf16_f32 v0, v64, s0
	v_cvt_pk_bf16_f32 v4, v65, s0
	v_pk_add_f32 v[94:95], v[96:97], v[92:93] neg_lo:[0,1] neg_hi:[0,1]
	v_pk_add_f32 v[92:93], v[96:97], v[92:93]
	v_perm_b32 v61, v23, v20, s41
	v_cvt_pk_bf16_f32 v20, v62, s0
	v_perm_b32 v62, v4, v0, s41
	v_mov_b32_e32 v96, v94
	v_mov_b32_e32 v97, v93
	v_mul_f32_e32 v0, v81, v93
	v_pk_mov_b32 v[86:87], v[80:81], v[82:83] op_sel:[1,0]
	v_pk_fma_f32 v[84:85], v[84:85], v[96:97], v[0:1] op_sel_hi:[1,1,0] neg_lo:[0,0,1] neg_hi:[0,0,1]
	v_mul_f32_e32 v0, v82, v93
	v_pk_fma_f32 v[86:87], v[86:87], v[96:97], v[0:1] op_sel_hi:[1,1,0]
	v_mul_f32_e32 v0, v67, v78
	v_pk_mul_f32 v[68:69], v[68:69], v[78:79]
	v_and_b32_e32 v103, 0xffff0000, v71
	v_lshlrev_b32_e32 v102, 16, v71
	v_fmac_f32_e32 v0, v76, v75
	v_sub_f32_e32 v4, v68, v69
	v_and_b32_e32 v97, 0xffff0000, v72
	v_lshlrev_b32_e32 v96, 16, v72
	v_and_b32_e32 v99, 0xffff0000, v70
	v_lshlrev_b32_e32 v98, 16, v70
	v_and_b32_e32 v101, 0xffff0000, v73
	v_lshlrev_b32_e32 v100, 16, v73
	v_pk_mul_f32 v[72:73], v[86:87], v[102:103] op_sel_hi:[0,1]
	v_cvt_pk_bf16_f32 v23, v63, s0
	v_cndmask_b32_e32 v4, v4, v78, vcc
	v_cndmask_b32_e32 v0, v0, v75, vcc
	v_pk_mul_f32 v[70:71], v[86:87], v[98:99] op_sel_hi:[0,1]
	v_pk_fma_f32 v[72:73], v[84:85], v[100:101], v[72:73] op_sel_hi:[0,1,1] neg_lo:[0,0,1] neg_hi:[0,0,1]
	v_pk_mul_f32 v[74:75], v[86:87], v[100:101] op_sel_hi:[0,1]
	v_perm_b32 v63, v23, v20, s41
	v_mov_b32_e32 v64, v8
	v_mov_b32_e32 v65, v8
	v_cndmask_b32_e64 v4, v4, v76, s[2:3]
	v_cndmask_b32_e64 v0, v0, v67, s[2:3]
	v_pk_fma_f32 v[70:71], v[84:85], v[96:97], v[70:71] op_sel_hi:[0,1,1] neg_lo:[0,0,1] neg_hi:[0,0,1]
	v_cvt_pk_bf16_f32 v8, v72, s0
	v_cvt_pk_bf16_f32 v20, v73, s0
	v_pk_mul_f32 v[72:73], v[86:87], v[96:97] op_sel_hi:[0,1]
	v_pk_fma_f32 v[74:75], v[84:85], v[102:103], v[74:75] op_sel_hi:[0,1,1]
	v_pk_mul_f32 v[76:77], v[92:93], v[102:103] op_sel:[1,0]
	v_cndmask_b32_e64 v66, v4, 1.0, s[4:5]
	v_cndmask_b32_e64 v69, v0, 0, s[4:5]
	v_cvt_pk_bf16_f32 v0, v70, s0
	v_cvt_pk_bf16_f32 v4, v71, s0
	v_perm_b32 v71, v20, v8, s41
	v_pk_fma_f32 v[72:73], v[84:85], v[98:99], v[72:73] op_sel_hi:[0,1,1]
	v_cvt_pk_bf16_f32 v8, v74, s0
	v_cvt_pk_bf16_f32 v20, v75, s0
	v_pk_mul_f32 v[74:75], v[92:93], v[98:99] op_sel:[1,0]
	v_pk_fma_f32 v[76:77], v[94:95], v[100:101], v[76:77] op_sel_hi:[0,1,1] neg_lo:[0,0,1] neg_hi:[0,0,1]
	v_pk_mul_f32 v[78:79], v[92:93], v[100:101] op_sel:[1,0]
	v_perm_b32 v70, v4, v0, s41
	v_cvt_pk_bf16_f32 v0, v72, s0
	v_cvt_pk_bf16_f32 v4, v73, s0
	v_perm_b32 v73, v20, v8, s41
	v_pk_fma_f32 v[74:75], v[94:95], v[96:97], v[74:75] op_sel_hi:[0,1,1] neg_lo:[0,0,1] neg_hi:[0,0,1]
	v_cvt_pk_bf16_f32 v8, v76, s0
	v_cvt_pk_bf16_f32 v20, v77, s0
	v_pk_mul_f32 v[76:77], v[92:93], v[96:97] op_sel:[1,0]
	v_pk_fma_f32 v[78:79], v[94:95], v[102:103], v[78:79] op_sel_hi:[0,1,1]
	v_pk_mul_f32 v[84:85], v[80:81], v[102:103] op_sel:[1,0]
	v_perm_b32 v72, v4, v0, s41
	v_cvt_pk_bf16_f32 v0, v74, s0
	v_cvt_pk_bf16_f32 v4, v75, s0
	v_perm_b32 v75, v20, v8, s41
	v_pk_fma_f32 v[76:77], v[94:95], v[98:99], v[76:77] op_sel_hi:[0,1,1]
	v_cvt_pk_bf16_f32 v8, v78, s0
	v_cvt_pk_bf16_f32 v20, v79, s0
	v_pk_fma_f32 v[84:85], v[82:83], v[100:101], v[84:85] op_sel_hi:[0,1,1] neg_lo:[0,0,1] neg_hi:[0,0,1]
	s_waitcnt vmcnt(4)
; __device__ __forceinline__ unsigned pk2(float lo, float hi) { f32x2 v = {lo, hi}; nbf2 r = __builtin_convertvector(v, nbf2); return __builtin_bit_cast(unsigned, r); }
; __device__ __forceinline__ bf16x4 cscale_bf(const bf16x4 re, const bf16x4 im, float wr, float wi, bool want_im) {
;     bf16x4 o;
; #pragma unroll
;     for (int k = 0; k < 4; k += 2) {
;         const float r0 = __uint_as_float((unsigned)(unsigned short)re[k] << 16), r1 = __uint_as_float((unsigned)(unsigned short)re[k + 1] << 16);
;         const float i0 = __uint_as_float((unsigned)(unsigned short)im[k] << 16), i1 = __uint_as_float((unsigned)(unsigned short)im[k + 1] << 16);
;         const unsigned w = want_im ? pk2(wr * i0 + wi * r0, wr * i1 + wi * r1) : pk2(wr * r0 - wi * i0, wr * r1 - wi * i1);
;         o[k] = (short)(w & 0xffffu); o[k + 1] = (short)(w >> 16);
;     }
;     return o;
; }
; template <int DIR>
; __device__ __forceinline__ void s5_local_dir(const bf16_t* UZ, unsigned char* ws, int gw, int NGW, int lane) {
;     ...
;     for (int t = 0; t < 4; ++t) {
;         const int p = 16 * t + fr;
;         const bf16x4 b_re = *(const bf16x4*)(Bb + (2 * p) * 16 + 4 * fq), b_im = *(const bf16x4*)(Bb + (2 * p + 1) * 16 + 4 * fq);
;         const f32x4 ap = ((const f32x4*)(ws + WS_APOW))[pair * 64 + p];
;         const float ar = ap.x, ai = ap.y;
;         float r2 = ar, i2 = ai; cmul(r2, i2, ar, ai);
;         float r4 = r2, i4 = i2; cmul(r4, i4, r2, i2);
;         float r8 = r4, i8 = i4; cmul(r8, i8, r4, i4);
;         float r12 = r8, i12 = i8; cmul(r12, i12, r4, i4);
;         float r16 = r8, i16 = i8; cmul(r16, i16, r8, i8);
;         float r32 = r16, i32 = i16; cmul(r32, i32, r16, i16);
;         float r48 = r32, i48 = i32; cmul(r48, i48, r16, i16);
;         a1r[t] = ar; a1i[t] = ai; a64r[t] = ap.z; a64i[t] = ap.w;
;         const int e = DIR ? fq : 3 - fq;
;         wr_[t] = e == 0 ? 1.f : e == 1 ? r4 : e == 2 ? r8 : r12; wi_[t] = e == 0 ? 0.f : e == 1 ? i4 : e == 2 ? i8 : i12;
; #pragma unroll
;         for (int m = 0; m < 4; ++m) {
;             const int em = DIR ? m : 3 - m;
;             const float pr = em == 0 ? 1.f : em == 1 ? r16 : em == 2 ? r32 : r48, pi = em == 0 ? 0.f : em == 1 ? i16 : em == 2 ? i32 : i48;
;             Bre[m][t] = cscale_bf(b_re, b_im, pr, pi, false); Bim[m][t] = cscale_bf(b_re, b_im, pr, pi, true);
;         }
	v_pk_mul_f32 v[92:93], v[12:13], v[12:13] op_sel:[1,1] op_sel_hi:[1,0]
	v_perm_b32 v74, v4, v0, s41
	v_cvt_pk_bf16_f32 v4, v77, s0
	v_perm_b32 v77, v20, v8, s41
	v_pk_mul_f32 v[78:79], v[80:81], v[98:99] op_sel:[1,0]
	v_cvt_pk_bf16_f32 v8, v84, s0
	v_cvt_pk_bf16_f32 v20, v85, s0
	v_pk_mul_f32 v[84:85], v[80:81], v[96:97] op_sel:[1,0]
	v_pk_mul_f32 v[80:81], v[80:81], v[100:101] op_sel:[1,0]
	v_pk_fma_f32 v[94:95], v[12:13], v[12:13], v[92:93] op_sel_hi:[1,0,1] neg_lo:[0,0,1] neg_hi:[0,0,1]
	v_pk_fma_f32 v[92:93], v[12:13], v[12:13], v[92:93] op_sel_hi:[1,0,1]
	v_pk_fma_f32 v[78:79], v[82:83], v[96:97], v[78:79] op_sel_hi:[0,1,1] neg_lo:[0,0,1] neg_hi:[0,0,1]
	v_pk_fma_f32 v[80:81], v[82:83], v[102:103], v[80:81] op_sel_hi:[0,1,1]
	v_pk_fma_f32 v[82:83], v[82:83], v[98:99], v[84:85] op_sel_hi:[0,1,1]
	v_xor_b32_e32 v85, 0x80000000, v99
	v_xor_b32_e32 v84, 0x80000000, v98
	v_pk_fma_f32 v[86:87], v[96:97], 0, v[98:99] op_sel_hi:[1,0,1]
	v_pk_mov_b32 v[98:99], v[92:93], v[94:95] op_sel:[1,0]
	v_pk_fma_f32 v[84:85], v[84:85], 0, v[96:97] op_sel_hi:[1,0,1]
	v_mov_b32_e32 v96, v94
	v_mov_b32_e32 v97, v93
	v_pk_mul_f32 v[92:93], v[92:93], v[98:99] op_sel:[1,0]
	v_cvt_pk_bf16_f32 v0, v76, s0
	v_pk_fma_f32 v[98:99], v[94:95], v[96:97], v[92:93] op_sel_hi:[0,1,1] neg_lo:[0,0,1] neg_hi:[0,0,1]
	v_pk_fma_f32 v[92:93], v[94:95], v[96:97], v[92:93] op_sel_hi:[0,1,1]
	v_perm_b32 v76, v4, v0, s41
	v_cvt_pk_bf16_f32 v0, v78, s0
	v_cvt_pk_bf16_f32 v4, v79, s0
	v_pk_mov_b32 v[96:97], v[92:93], v[98:99] op_sel:[1,0]
	v_perm_b32 v78, v4, v0, s41
	v_cvt_pk_bf16_f32 v0, v82, s0
	v_cvt_pk_bf16_f32 v4, v83, s0
	v_xor_b32_e32 v83, 0x80000000, v103
	v_xor_b32_e32 v82, 0x80000000, v102
	v_mov_b32_e32 v94, v98
	v_mov_b32_e32 v95, v93
	v_pk_mul_f32 v[96:97], v[92:93], v[96:97] op_sel:[1,0]
	v_perm_b32 v79, v20, v8, s41
	v_cvt_pk_bf16_f32 v8, v80, s0
	v_perm_b32 v80, v4, v0, s41
	v_pk_fma_f32 v[82:83], v[82:83], 0, v[100:101] op_sel_hi:[1,0,1]
	v_cvt_pk_bf16_f32 v0, v84, s0
	v_cvt_pk_bf16_f32 v4, v85, s0
	v_pk_fma_f32 v[84:85], v[100:101], 0, v[102:103] op_sel_hi:[1,0,1]
	v_pk_fma_f32 v[100:101], v[98:99], v[94:95], v[96:97] op_sel_hi:[0,1,1] neg_lo:[0,0,1] neg_hi:[0,0,1]
	v_pk_fma_f32 v[96:97], v[98:99], v[94:95], v[96:97] op_sel_hi:[0,1,1]
	v_mov_b32_e32 v101, v97
	v_pk_mul_f32 v[102:103], v[100:101], v[100:101]
	v_pk_mul_f32 v[104:105], v[96:97], v[100:101] op_sel:[1,0] op_sel_hi:[0,1]
	v_mov_b32_e32 v106, v102
	v_mov_b32_e32 v107, v104
	v_pk_mov_b32 v[102:103], v[102:103], v[104:105] op_sel:[1,0]
	v_cvt_pk_bf16_f32 v20, v81, s0
	v_pk_add_f32 v[104:105], v[106:107], v[102:103] neg_lo:[0,1] neg_hi:[0,1]
	v_pk_add_f32 v[102:103], v[106:107], v[102:103]
	v_mov_b32_e32 v106, v104
	v_mov_b32_e32 v107, v103
	v_pk_mul_f32 v[110:111], v[106:107], v[106:107]
	v_pk_mul_f32 v[112:113], v[102:103], v[106:107] op_sel:[1,0] op_sel_hi:[0,1]
	v_mov_b32_e32 v114, v110
	v_mov_b32_e32 v115, v112
	v_pk_mov_b32 v[110:111], v[110:111], v[112:113] op_sel:[1,0]
	v_perm_b32 v81, v20, v8, s41
	v_cvt_pk_bf16_f32 v8, v82, s0
	v_cvt_pk_bf16_f32 v20, v83, s0
	v_perm_b32 v82, v4, v0, s41
	v_cvt_pk_bf16_f32 v0, v86, s0
	v_cvt_pk_bf16_f32 v4, v87, s0
	v_pk_add_f32 v[112:113], v[114:115], v[110:111] neg_lo:[0,1] neg_hi:[0,1]
	v_pk_add_f32 v[110:111], v[114:115], v[110:111]
	v_perm_b32 v83, v20, v8, s41
	v_cvt_pk_bf16_f32 v8, v84, s0
	v_perm_b32 v84, v4, v0, s41
	v_mov_b32_e32 v114, v112
	v_mov_b32_e32 v115, v111
	v_mul_f32_e32 v0, v103, v111
	v_pk_mov_b32 v[108:109], v[102:103], v[104:105] op_sel:[1,0]
	v_pk_fma_f32 v[106:107], v[106:107], v[114:115], v[0:1] op_sel_hi:[1,1,0] neg_lo:[0,0,1] neg_hi:[0,0,1]
	v_mul_f32_e32 v0, v104, v111
	v_pk_fma_f32 v[108:109], v[108:109], v[114:115], v[0:1] op_sel_hi:[1,1,0]
	v_mul_f32_e32 v0, v93, v100
	v_pk_mul_f32 v[94:95], v[94:95], v[100:101]
	v_and_b32_e32 v123, 0xffff0000, v91
	v_lshlrev_b32_e32 v122, 16, v91
	v_fmac_f32_e32 v0, v98, v97
	v_sub_f32_e32 v4, v94, v95
	v_and_b32_e32 v119, 0xffff0000, v90
	v_lshlrev_b32_e32 v118, 16, v90
	v_and_b32_e32 v121, 0xffff0000, v89
	v_lshlrev_b32_e32 v120, 16, v89
	v_pk_mul_f32 v[90:91], v[108:109], v[122:123] op_sel_hi:[0,1]
	v_cvt_pk_bf16_f32 v20, v85, s0
	v_cndmask_b32_e32 v4, v4, v100, vcc
	v_cndmask_b32_e32 v0, v0, v97, vcc
	v_and_b32_e32 v117, 0xffff0000, v88
	v_lshlrev_b32_e32 v116, 16, v88
	v_pk_mul_f32 v[88:89], v[108:109], v[118:119] op_sel_hi:[0,1]
	v_pk_fma_f32 v[90:91], v[106:107], v[120:121], v[90:91] op_sel_hi:[0,1,1] neg_lo:[0,0,1] neg_hi:[0,0,1]
	v_pk_mul_f32 v[96:97], v[108:109], v[120:121] op_sel_hi:[0,1]
	v_perm_b32 v85, v20, v8, s41
	v_mov_b32_e32 v86, v12
	v_mov_b32_e32 v87, v12
	v_cndmask_b32_e64 v4, v4, v98, s[2:3]
	v_cndmask_b32_e64 v0, v0, v93, s[2:3]
	v_pk_fma_f32 v[88:89], v[106:107], v[116:117], v[88:89] op_sel_hi:[0,1,1] neg_lo:[0,0,1] neg_hi:[0,0,1]
	v_cvt_pk_bf16_f32 v8, v90, s0
	v_cvt_pk_bf16_f32 v12, v91, s0
	v_pk_mul_f32 v[90:91], v[108:109], v[116:117] op_sel_hi:[0,1]
	v_pk_fma_f32 v[96:97], v[106:107], v[122:123], v[96:97] op_sel_hi:[0,1,1]
	v_pk_mul_f32 v[98:99], v[110:111], v[122:123] op_sel:[1,0]
	v_cndmask_b32_e64 v92, v4, 1.0, s[4:5]
	v_cndmask_b32_e64 v95, v0, 0, s[4:5]
	v_cvt_pk_bf16_f32 v0, v88, s0
	v_cvt_pk_bf16_f32 v4, v89, s0
	v_perm_b32 v89, v12, v8, s41
	v_pk_fma_f32 v[90:91], v[106:107], v[118:119], v[90:91] op_sel_hi:[0,1,1]
	v_cvt_pk_bf16_f32 v8, v96, s0
	v_cvt_pk_bf16_f32 v12, v97, s0
	v_pk_mul_f32 v[96:97], v[110:111], v[118:119] op_sel:[1,0]
	v_pk_fma_f32 v[98:99], v[112:113], v[120:121], v[98:99] op_sel_hi:[0,1,1] neg_lo:[0,0,1] neg_hi:[0,0,1]
	v_pk_mul_f32 v[100:101], v[110:111], v[120:121] op_sel:[1,0]
	v_perm_b32 v88, v4, v0, s41
	v_cvt_pk_bf16_f32 v0, v90, s0
; __device__ __forceinline__ bf16x4 cscale_bf(const bf16x4 re, const bf16x4 im, float wr, float wi, bool want_im) {
;     bf16x4 o;
; #pragma unroll
;     for (int k = 0; k < 4; k += 2) {
;         const float r0 = __uint_as_float((unsigned)(unsigned short)re[k] << 16), r1 = __uint_as_float((unsigned)(unsigned short)re[k + 1] << 16);
;         const float i0 = __uint_as_float((unsigned)(unsigned short)im[k] << 16), i1 = __uint_as_float((unsigned)(unsigned short)im[k + 1] << 16);
;         const unsigned w = want_im ? pk2(wr * i0 + wi * r0, wr * i1 + wi * r1) : pk2(wr * r0 - wi * i0, wr * r1 - wi * i1);
;         o[k] = (short)(w & 0xffffu); o[k + 1] = (short)(w >> 16);
;     }
;     return o;
; }
; template <int DIR>
; __device__ __forceinline__ void s5_local_dir(const bf16_t* UZ, unsigned char* ws, int gw, int NGW, int lane) {
;     ...
;     for (int t = 0; t < 4; ++t) {
;         const int p = 16 * t + fr;
;         const bf16x4 b_re = *(const bf16x4*)(Bb + (2 * p) * 16 + 4 * fq), b_im = *(const bf16x4*)(Bb + (2 * p + 1) * 16 + 4 * fq);
;         const f32x4 ap = ((const f32x4*)(ws + WS_APOW))[pair * 64 + p];
;         const float ar = ap.x, ai = ap.y;
;         float r2 = ar, i2 = ai; cmul(r2, i2, ar, ai);
;         float r4 = r2, i4 = i2; cmul(r4, i4, r2, i2);
;         float r8 = r4, i8 = i4; cmul(r8, i8, r4, i4);
;         float r12 = r8, i12 = i8; cmul(r12, i12, r4, i4);
;         float r16 = r8, i16 = i8; cmul(r16, i16, r8, i8);
;         float r32 = r16, i32 = i16; cmul(r32, i32, r16, i16);
;         float r48 = r32, i48 = i32; cmul(r48, i48, r16, i16);
;         a1r[t] = ar; a1i[t] = ai; a64r[t] = ap.z; a64i[t] = ap.w;
;         const int e = DIR ? fq : 3 - fq;
;         wr_[t] = e == 0 ? 1.f : e == 1 ? r4 : e == 2 ? r8 : r12; wi_[t] = e == 0 ? 0.f : e == 1 ? i4 : e == 2 ? i8 : i12;
; #pragma unroll
;         for (int m = 0; m < 4; ++m) {
;             const int em = DIR ? m : 3 - m;
;             const float pr = em == 0 ? 1.f : em == 1 ? r16 : em == 2 ? r32 : r48, pi = em == 0 ? 0.f : em == 1 ? i16 : em == 2 ? i32 : i48;
;             Bre[m][t] = cscale_bf(b_re, b_im, pr, pi, false); Bim[m][t] = cscale_bf(b_re, b_im, pr, pi, true);
;         }
;     ...
;     load_uf(Un, UZ, chunk_rowbase(b, DIR, c0), g, lane);
;     for (int c = c0; c < c1; ++c) {
;         bf16x4 Uf[4];
; #pragma unroll
;         for (int m = 0; m < 4; ++m) Uf[m] = Un[m];
	v_cvt_pk_bf16_f32 v4, v91, s0
	v_perm_b32 v91, v12, v8, s41
	v_pk_fma_f32 v[96:97], v[112:113], v[116:117], v[96:97] op_sel_hi:[0,1,1] neg_lo:[0,0,1] neg_hi:[0,0,1]
	v_cvt_pk_bf16_f32 v8, v98, s0
	v_cvt_pk_bf16_f32 v12, v99, s0
	v_pk_mul_f32 v[98:99], v[110:111], v[116:117] op_sel:[1,0]
	v_pk_fma_f32 v[100:101], v[112:113], v[122:123], v[100:101] op_sel_hi:[0,1,1]
	v_pk_mul_f32 v[106:107], v[102:103], v[122:123] op_sel:[1,0]
	v_perm_b32 v90, v4, v0, s41
	v_cvt_pk_bf16_f32 v0, v96, s0
	v_cvt_pk_bf16_f32 v4, v97, s0
	v_perm_b32 v97, v12, v8, s41
	v_pk_fma_f32 v[98:99], v[112:113], v[118:119], v[98:99] op_sel_hi:[0,1,1]
	v_cvt_pk_bf16_f32 v8, v100, s0
	v_cvt_pk_bf16_f32 v12, v101, s0
	v_pk_fma_f32 v[106:107], v[104:105], v[120:121], v[106:107] op_sel_hi:[0,1,1] neg_lo:[0,0,1] neg_hi:[0,0,1]
	v_perm_b32 v96, v4, v0, s41
	v_cvt_pk_bf16_f32 v4, v99, s0
	v_perm_b32 v99, v12, v8, s41
	v_pk_mul_f32 v[100:101], v[102:103], v[118:119] op_sel:[1,0]
	v_cvt_pk_bf16_f32 v8, v106, s0
	v_cvt_pk_bf16_f32 v12, v107, s0
	v_pk_mul_f32 v[106:107], v[102:103], v[116:117] op_sel:[1,0]
	v_pk_mul_f32 v[102:103], v[102:103], v[120:121] op_sel:[1,0]
	v_pk_fma_f32 v[100:101], v[104:105], v[116:117], v[100:101] op_sel_hi:[0,1,1] neg_lo:[0,0,1] neg_hi:[0,0,1]
	v_pk_fma_f32 v[102:103], v[104:105], v[122:123], v[102:103] op_sel_hi:[0,1,1]
	v_pk_fma_f32 v[104:105], v[104:105], v[118:119], v[106:107] op_sel_hi:[0,1,1]
	v_add_u32_e32 v106, s25, v127
	v_ashrrev_i32_e32 v107, 31, v106
	v_lshlrev_b64 v[106:107], 12, v[106:107]
	v_lshl_add_u64 v[106:107], v[16:17], 0, v[106:107]
	s_mov_b32 s2, 0x10000
	v_add_co_u32_e32 v124, vcc, s2, v106
	s_mov_b32 s2, 0x20000
	s_nop 0
	v_addc_co_u32_e32 v125, vcc, 0, v107, vcc
	v_add_co_u32_e32 v128, vcc, s2, v106
	s_mov_b32 s2, 0x30000
	s_nop 0
	v_addc_co_u32_e32 v129, vcc, 0, v107, vcc
	v_add_co_u32_e32 v130, vcc, s2, v106
	v_cvt_pk_bf16_f32 v0, v98, s0
	s_nop 0
	v_addc_co_u32_e32 v131, vcc, 0, v107, vcc
	s_waitcnt vmcnt(0)
; template <int DIR>
; __device__ __forceinline__ void s5_local_dir(const bf16_t* UZ, unsigned char* ws, int gw, int NGW, int lane) {
;     ...
;         a1r[t] = ar; a1i[t] = ai; a64r[t] = ap.z; a64i[t] = ap.w;
;         const int e = DIR ? fq : 3 - fq;
;         wr_[t] = e == 0 ? 1.f : e == 1 ? r4 : e == 2 ? r8 : r12; wi_[t] = e == 0 ? 0.f : e == 1 ? i4 : e == 2 ? i8 : i12;
; #pragma unroll
;         for (int m = 0; m < 4; ++m) {
;             const int em = DIR ? m : 3 - m;
;             const float pr = em == 0 ? 1.f : em == 1 ? r16 : em == 2 ? r32 : r48, pi = em == 0 ? 0.f : em == 1 ? i16 : em == 2 ? i32 : i48;
;             Bre[m][t] = cscale_bf(b_re, b_im, pr, pi, false); Bim[m][t] = cscale_bf(b_re, b_im, pr, pi, true);
;         }
;     }
;     const int qd = gw >> 7, b = qd >> 2, q = qd & 3;
;     if (qd >= 16) return;
;     const int c0 = 17 * q, c1 = q < 3 ? c0 + 17 : 67;
;     float Rr[4] = {0.f, 0.f, 0.f, 0.f}, Ri[4] = {0.f, 0.f, 0.f, 0.f};
;     float* ebase = E + ((size_t)((b * 2 + DIR) * 64 + g) * NCHUNK) * 128;
;     bf16x4 Un[4];
;     load_uf(Un, UZ, chunk_rowbase(b, DIR, c0), g, lane);
;     for (int c = c0; c < c1; ++c) {
;         bf16x4 Uf[4];
; #pragma unroll
;         for (int m = 0; m < 4; ++m) Uf[m] = Un[m];
;         if (c + 1 < c1) load_uf(Un, UZ, chunk_rowbase(b, DIR, c + 1), g, lane);
;         float* e = ebase + (size_t)c * 128;
	v_mov_b64_e32 v[108:109], v[152:153]
	v_mov_b64_e32 v[112:113], v[154:155]
	v_mov_b64_e32 v[114:115], v[156:157]
	v_mov_b64_e32 v[110:111], v[158:159]
	v_perm_b32 v98, v4, v0, s41
	v_cvt_pk_bf16_f32 v0, v100, s0
	v_cvt_pk_bf16_f32 v4, v101, s0
	v_xor_b32_e32 v107, 0x80000000, v119
	v_xor_b32_e32 v106, 0x80000000, v118
	v_perm_b32 v100, v4, v0, s41
	v_cvt_pk_bf16_f32 v0, v104, s0
	v_cvt_pk_bf16_f32 v4, v105, s0
	v_xor_b32_e32 v105, 0x80000000, v123
	v_xor_b32_e32 v104, 0x80000000, v122
	v_pk_fma_f32 v[106:107], v[106:107], 0, v[116:117] op_sel_hi:[1,0,1]
	v_perm_b32 v101, v12, v8, s41
	v_cvt_pk_bf16_f32 v8, v102, s0
	v_cvt_pk_bf16_f32 v12, v103, s0
	v_perm_b32 v102, v4, v0, s41
	v_pk_fma_f32 v[104:105], v[104:105], 0, v[120:121] op_sel_hi:[1,0,1]
	v_cvt_pk_bf16_f32 v0, v106, s0
	v_cvt_pk_bf16_f32 v4, v107, s0
	v_pk_fma_f32 v[116:117], v[116:117], 0, v[118:119] op_sel_hi:[1,0,1]
	v_perm_b32 v103, v12, v8, s41
	v_cvt_pk_bf16_f32 v8, v104, s0
	v_cvt_pk_bf16_f32 v12, v105, s0
	v_perm_b32 v104, v4, v0, s41
	v_pk_fma_f32 v[106:107], v[120:121], 0, v[122:123] op_sel_hi:[1,0,1]
	v_cvt_pk_bf16_f32 v0, v116, s0
	v_cvt_pk_bf16_f32 v4, v117, s0
	v_perm_b32 v105, v12, v8, s41
	v_cvt_pk_bf16_f32 v8, v106, s0
	v_perm_b32 v106, v4, v0, s41
	v_mbcnt_lo_u32_b32 v0, -1, 0
	v_cvt_pk_bf16_f32 v12, v107, s0
	v_mbcnt_hi_u32_b32 v0, -1, v0
	v_perm_b32 v107, v12, v8, s41
	s_lshl_b32 s41, s23, 12
	s_lshl_b32 s42, s23, 8
	v_and_b32_e32 v8, 64, v0
	s_add_i32 s4, s38, s36
	s_bfe_u32 s23, s40, 0x20007
	s_addk_i32 s41, 0xff00
	s_addk_i32 s42, 0x4000
	v_xor_b32_e32 v4, 16, v0
	v_add_u32_e32 v8, 64, v8
	s_mul_hi_i32 s5, s4, 0x8800
	s_mul_i32 s4, s4, 0x8800
	s_mulk_i32 s23, 0x2200
	v_cmp_lt_i32_e32 vcc, v4, v8
	s_add_u32 s4, s4, s23
	s_addc_u32 s5, s5, 0
	v_cndmask_b32_e32 v4, v0, v4, vcc
	v_lshlrev_b32_e32 v128, 2, v4
	v_xor_b32_e32 v4, 32, v0
	s_add_u32 s4, s30, s4
	v_cmp_lt_i32_e32 vcc, v4, v8
	v_lshlrev_b32_e32 v20, 2, v126
	s_addc_u32 s5, s31, s5
	v_cndmask_b32_e32 v0, v0, v4, vcc
	v_lshl_add_u64 v[116:117], s[4:5], 0, v[20:21]
	s_mov_b64 s[4:5], 0x1700100
	v_or_b32_e32 v20, s22, v127
	v_lshlrev_b32_e32 v129, 2, v0
	v_cmp_gt_u32_e64 s[2:3], 16, v126
	v_xor_b32_e32 v0, 0x80000000, v1
	v_mov_b32_e32 v23, v22
	v_xor_b32_e32 v24, 0x80000000, v25
	v_xor_b32_e32 v4, 0x80000000, v5
	v_mov_b32_e32 v45, v44
	v_xor_b32_e32 v46, 0x80000000, v47
	v_xor_b32_e32 v8, 0x80000000, v9
	v_mov_b32_e32 v67, v66
	v_xor_b32_e32 v68, 0x80000000, v69
	v_xor_b32_e32 v12, 0x80000000, v13
	v_mov_b32_e32 v93, v92
	v_xor_b32_e32 v94, 0x80000000, v95
	v_lshl_add_u64 v[116:117], v[116:117], 0, s[4:5]
	v_add_u32_e32 v20, 0x70, v20
	s_mov_b64 s[4:5], 0x200
	v_mov_b32_e32 v133, v21
	v_mov_b32_e32 v131, v21
	v_mov_b32_e32 v127, v21
	v_mov_b32_e32 v135, v21
	v_mov_b32_e32 v134, v21
	v_mov_b32_e32 v132, v21
	v_mov_b32_e32 v130, v21
	v_and_b32_e32 v244, 16, v126
	v_and_b32_e32 v245, 32, v126
	v_cmp_ne_u32_e64 s[96:97], 0, v244
	v_cmp_ne_u32_e32 vcc, 0, v245
	s_nop 1
	v_cndmask_b32_e32 v244, v2, v10, vcc
	v_cndmask_b32_e32 v245, v6, v14, vcc
	v_cndmask_b32_e64 v242, v244, v245, s[96:97]
	v_cndmask_b32_e32 v244, v3, v11, vcc
	v_cndmask_b32_e32 v245, v7, v15, vcc
	v_cndmask_b32_e64 v243, v244, v245, s[96:97]
	v_mov_b64_e32 v[152:153], v[26:27]
	v_mov_b64_e32 v[154:155], v[28:29]
	v_mov_b64_e32 v[156:157], v[30:31]
	v_mov_b64_e32 v[158:159], v[32:33]
	v_mov_b64_e32 v[160:161], v[34:35]
	v_mov_b64_e32 v[162:163], v[36:37]
	v_mov_b64_e32 v[164:165], v[38:39]
	v_mov_b64_e32 v[166:167], v[40:41]
	v_mov_b64_e32 v[26:27], v[152:153]
	v_mov_b64_e32 v[28:29], v[164:165]
	v_mov_b64_e32 v[30:31], v[156:157]
	v_mov_b64_e32 v[32:33], v[160:161]
	v_mov_b64_e32 v[34:35], v[154:155]
	v_mov_b64_e32 v[36:37], v[166:167]
	v_mov_b64_e32 v[38:39], v[158:159]
	v_mov_b64_e32 v[40:41], v[162:163]
	v_mov_b64_e32 v[152:153], v[48:49]
	v_mov_b64_e32 v[154:155], v[50:51]
	v_mov_b64_e32 v[156:157], v[52:53]
	v_mov_b64_e32 v[158:159], v[54:55]
	v_mov_b64_e32 v[160:161], v[56:57]
	v_mov_b64_e32 v[162:163], v[58:59]
	v_mov_b64_e32 v[164:165], v[60:61]
	v_mov_b64_e32 v[166:167], v[62:63]
	v_mov_b64_e32 v[48:49], v[152:153]
	v_mov_b64_e32 v[50:51], v[164:165]
	v_mov_b64_e32 v[52:53], v[156:157]
	v_mov_b64_e32 v[54:55], v[160:161]
	v_mov_b64_e32 v[56:57], v[154:155]
	v_mov_b64_e32 v[58:59], v[166:167]
	v_mov_b64_e32 v[60:61], v[158:159]
	v_mov_b64_e32 v[62:63], v[162:163]
	v_mov_b64_e32 v[152:153], v[70:71]
	v_mov_b64_e32 v[154:155], v[72:73]
	v_mov_b64_e32 v[156:157], v[74:75]
	v_mov_b64_e32 v[158:159], v[76:77]
	v_mov_b64_e32 v[160:161], v[78:79]
	v_mov_b64_e32 v[162:163], v[80:81]
	v_mov_b64_e32 v[164:165], v[82:83]
	v_mov_b64_e32 v[166:167], v[84:85]
	v_mov_b64_e32 v[70:71], v[152:153]
	v_mov_b64_e32 v[72:73], v[164:165]
	v_mov_b64_e32 v[74:75], v[156:157]
	v_mov_b64_e32 v[76:77], v[160:161]
	v_mov_b64_e32 v[78:79], v[154:155]
	v_mov_b64_e32 v[80:81], v[166:167]
	v_mov_b64_e32 v[82:83], v[158:159]
	v_mov_b64_e32 v[84:85], v[162:163]
	v_mov_b64_e32 v[152:153], v[88:89]
	v_mov_b64_e32 v[154:155], v[90:91]
	v_mov_b64_e32 v[156:157], v[96:97]
	v_mov_b64_e32 v[158:159], v[98:99]
	v_mov_b64_e32 v[160:161], v[100:101]
	v_mov_b64_e32 v[162:163], v[102:103]
	v_mov_b64_e32 v[164:165], v[104:105]
	v_mov_b64_e32 v[166:167], v[106:107]
	v_mov_b64_e32 v[88:89], v[152:153]
	v_mov_b64_e32 v[90:91], v[164:165]
	v_mov_b64_e32 v[96:97], v[156:157]
	v_mov_b64_e32 v[98:99], v[160:161]
	v_mov_b64_e32 v[100:101], v[154:155]
	v_mov_b64_e32 v[102:103], v[166:167]
	v_mov_b64_e32 v[104:105], v[158:159]
	v_mov_b64_e32 v[106:107], v[162:163]
	s_nop 1

; template <int DIR>
; __device__ __forceinline__ void s5_local_dir(const bf16_t* UZ, unsigned char* ws, int gw, int NGW, int lane) {
;     ...
; #pragma unroll
;         for (int t = 0; t < 4; ++t) {
;             f32x4 cr = {0.f, 0.f, 0.f, 0.f}, ci = {0.f, 0.f, 0.f, 0.f};
; #pragma unroll
;             for (int m = 0; m < 4; ++m) {
;                 cr = __builtin_amdgcn_mfma_f32_16x16x16bf16_1k(Uf[m], Bre[m][t], cr, 0, 0, 0);
;                 ci = __builtin_amdgcn_mfma_f32_16x16x16bf16_1k(Uf[m], Bim[m][t], ci, 0, 0, 0);
;             }
;             f32x2 s2 = {DIR ? cr[3] : cr[0], DIR ? ci[3] : ci[0]};
; #pragma unroll
;             for (int ii = 1; ii < 4; ++ii) { const int i = DIR ? 3 - ii : ii;
;                 s2 = cmac(s2, (f32x2){a1r[t], a1r[t]}, (f32x2){-a1i[t], a1i[t]}, (f32x2){cr[i], ci[i]}); }
;             s2 = cmac(s2, (f32x2){wr_[t], wr_[t]}, (f32x2){-wi_[t], wi_[t]}, (f32x2){0.f, 0.f});
;             float sr = s2.x, si = s2.y;
;             sr += __shfl_xor(sr, 16); si += __shfl_xor(si, 16); sr += __shfl_xor(sr, 32); si += __shfl_xor(si, 32);
;             if (fq == 0) { e[16 * t + fr] = Rr[t]; e[64 + 16 * t + fr] = Ri[t]; }
;             const float nr = fmaf(a64r[t], Rr[t], fmaf(-a64i[t], Ri[t], sr)), ni = fmaf(a64r[t], Ri[t], fmaf(a64i[t], Rr[t], si)); Rr[t] = nr; Ri[t] = ni;
;         }
;     }
.LBB0_674:
	global_store_dword v[116:117], v240, off offset:-256
	global_store_dword v[116:117], v241, off
	s_waitcnt vmcnt(9)
	v_mfma_f32_16x16x32_bf16 v[136:139], v[108:111], v[26:29], 0
	v_mfma_f32_16x16x32_bf16 v[140:143], v[108:111], v[34:37], 0
	v_mfma_f32_16x16x32_bf16 v[196:199], v[108:111], v[48:51], 0
	v_mfma_f32_16x16x32_bf16 v[200:203], v[108:111], v[56:59], 0
	v_mfma_f32_16x16x32_bf16 v[208:211], v[108:111], v[70:73], 0
	v_mfma_f32_16x16x32_bf16 v[212:215], v[108:111], v[78:81], 0
	v_mfma_f32_16x16x32_bf16 v[224:227], v[108:111], v[88:91], 0
	v_mfma_f32_16x16x32_bf16 v[184:187], v[108:111], v[100:103], 0
	v_mfma_f32_16x16x32_bf16 v[136:139], v[112:115], v[30:33], v[136:139]
	v_mfma_f32_16x16x32_bf16 v[140:143], v[112:115], v[38:41], v[140:143]
	v_mfma_f32_16x16x32_bf16 v[196:199], v[112:115], v[52:55], v[196:199]
	v_mfma_f32_16x16x32_bf16 v[200:203], v[112:115], v[60:63], v[200:203]
	v_mfma_f32_16x16x32_bf16 v[208:211], v[112:115], v[74:77], v[208:211]
	v_mfma_f32_16x16x32_bf16 v[212:215], v[112:115], v[82:85], v[212:215]
	v_mfma_f32_16x16x32_bf16 v[224:227], v[112:115], v[96:99], v[224:227]
	v_mfma_f32_16x16x32_bf16 v[184:187], v[112:115], v[104:107], v[184:187]
	s_nop 6
	v_mov_b32_e32 v144, v136
	v_mov_b32_e32 v204, v196
	v_mov_b32_e32 v216, v208
	v_mov_b32_e32 v228, v224
	v_mov_b32_e32 v145, v140
	v_mov_b32_e32 v205, v200
	v_mov_b32_e32 v217, v212
	v_mov_b32_e32 v229, v184
	v_mov_b32_e32 v146, v137
	v_mov_b32_e32 v206, v197
	v_mov_b32_e32 v218, v209
	v_mov_b32_e32 v188, v225
	v_mov_b32_e32 v147, v141
	v_mov_b32_e32 v207, v201
	v_mov_b32_e32 v219, v213
	v_mov_b32_e32 v189, v185
	v_pk_fma_f32 v[144:145], v[18:19], v[144:145], v[146:147]
	v_pk_fma_f32 v[204:205], v[42:43], v[204:205], v[206:207]
	v_pk_fma_f32 v[216:217], v[64:65], v[216:217], v[218:219]
	v_pk_fma_f32 v[188:189], v[86:87], v[228:229], v[188:189]
	v_mov_b32_e32 v141, v136
	v_mov_b32_e32 v201, v196
	v_mov_b32_e32 v213, v208
	v_mov_b32_e32 v185, v224
	v_pk_fma_f32 v[136:137], v[0:1], v[140:141], v[144:145]
	v_pk_fma_f32 v[196:197], v[4:5], v[200:201], v[204:205]
	v_pk_fma_f32 v[208:209], v[8:9], v[212:213], v[216:217]
	v_pk_fma_f32 v[184:185], v[12:13], v[184:185], v[188:189]
	v_mov_b32_e32 v140, v138
	v_mov_b32_e32 v200, v198
	v_mov_b32_e32 v212, v210
	v_mov_b32_e32 v188, v226
	v_mov_b32_e32 v141, v142
	v_mov_b32_e32 v201, v202
	v_mov_b32_e32 v213, v214
	v_mov_b32_e32 v189, v186
	v_pk_fma_f32 v[140:141], v[18:19], v[136:137], v[140:141]
	v_pk_fma_f32 v[200:201], v[42:43], v[196:197], v[200:201]
	v_pk_fma_f32 v[212:213], v[64:65], v[208:209], v[212:213]
	v_pk_fma_f32 v[188:189], v[86:87], v[184:185], v[188:189]
	v_mov_b32_e32 v142, v139
	v_mov_b32_e32 v202, v199
	v_mov_b32_e32 v214, v211
	v_mov_b32_e32 v186, v227
	v_pk_fma_f32 v[136:137], v[0:1], v[136:137], v[140:141] op_sel:[0,1,0] op_sel_hi:[1,0,1]
	v_pk_fma_f32 v[196:197], v[4:5], v[196:197], v[200:201] op_sel:[0,1,0] op_sel_hi:[1,0,1]
	v_pk_fma_f32 v[208:209], v[8:9], v[208:209], v[212:213] op_sel:[0,1,0] op_sel_hi:[1,0,1]
	v_pk_fma_f32 v[184:185], v[12:13], v[184:185], v[188:189] op_sel:[0,1,0] op_sel_hi:[1,0,1]
	s_nop 0
	s_nop 0
	s_nop 0
	s_nop 0
	v_pk_fma_f32 v[138:139], v[18:19], v[136:137], v[142:143]
	v_pk_fma_f32 v[198:199], v[42:43], v[196:197], v[202:203]
	v_pk_fma_f32 v[210:211], v[64:65], v[208:209], v[214:215]
	v_pk_fma_f32 v[186:187], v[86:87], v[184:185], v[186:187]
	s_nop 0
	s_nop 0
	s_nop 0
	s_nop 0
	v_pk_fma_f32 v[136:137], v[0:1], v[136:137], v[138:139] op_sel:[0,1,0] op_sel_hi:[1,0,1]
	v_pk_fma_f32 v[196:197], v[4:5], v[196:197], v[198:199] op_sel:[0,1,0] op_sel_hi:[1,0,1]
	v_pk_fma_f32 v[208:209], v[8:9], v[208:209], v[210:211] op_sel:[0,1,0] op_sel_hi:[1,0,1]
	v_pk_fma_f32 v[184:185], v[12:13], v[184:185], v[186:187] op_sel:[0,1,0] op_sel_hi:[1,0,1]
	s_nop 0
	s_nop 0
	s_nop 0
	s_nop 0
	v_pk_fma_f32 v[138:139], v[22:23], v[136:137], 0 op_sel_hi:[1,1,0]
	v_pk_fma_f32 v[198:199], v[44:45], v[196:197], 0 op_sel_hi:[1,1,0]
	v_pk_fma_f32 v[210:211], v[66:67], v[208:209], 0 op_sel_hi:[1,1,0]
	v_pk_fma_f32 v[186:187], v[92:93], v[184:185], 0 op_sel_hi:[1,1,0]
	s_nop 0
	s_nop 0
	s_nop 0
	s_nop 0
	v_pk_fma_f32 v[136:137], v[24:25], v[136:137], v[138:139] op_sel:[0,1,0] op_sel_hi:[1,0,1]
	v_pk_fma_f32 v[196:197], v[46:47], v[196:197], v[198:199] op_sel:[0,1,0] op_sel_hi:[1,0,1]
	v_pk_fma_f32 v[208:209], v[68:69], v[208:209], v[210:211] op_sel:[0,1,0] op_sel_hi:[1,0,1]
	v_pk_fma_f32 v[184:185], v[94:95], v[184:185], v[186:187] op_sel:[0,1,0] op_sel_hi:[1,0,1]
	s_nop 1
	v_permlane32_swap_b32_e32 v136, v208
	v_permlane32_swap_b32_e32 v137, v209
	v_permlane32_swap_b32_e32 v196, v184
	v_permlane32_swap_b32_e32 v197, v185
	v_add_f32_e32 v136, v136, v208
	v_add_f32_e32 v196, v196, v184
	v_add_f32_e32 v137, v137, v209
	v_add_f32_e32 v197, v197, v185
	s_nop 0
	v_permlane16_swap_b32_e32 v136, v196
	v_permlane16_swap_b32_e32 v137, v197
	v_add_f32_e32 v136, v136, v196
	v_add_f32_e32 v137, v137, v197
	v_fma_f32 v244, -v243, v241, v136
	v_fma_f32 v245, v243, v240, v137
	v_fma_f32 v240, v242, v240, v244
	v_fma_f32 v241, v242, v241, v245
	v_lshl_add_u64 v[116:117], v[116:117], 0, s[4:5]
	v_add_u32_e32 v20, 64, v20
	s_and_b64 vcc, exec, s[22:23]
	s_cbranch_vccnz .LBB0_702
	s_mov_b32 s24, s40
	s_waitcnt vmcnt(3)
	v_mov_b32_e32 v108, v118
	v_mov_b32_e32 v109, v119
	s_waitcnt vmcnt(2)
	v_mov_b32_e32 v112, v120
	v_mov_b32_e32 v113, v121
	s_waitcnt vmcnt(1)
	v_mov_b32_e32 v114, v122
	v_mov_b32_e32 v115, v123
	s_waitcnt vmcnt(0)
	v_mov_b32_e32 v110, v124
	v_mov_b32_e32 v111, v125
	s_branch .LBB0_671
